# all GEMM K-loops: accumulate-chain MFMA order (each accumulator's two K-half MFMAs back to back)
# speedup vs baseline: 1.0084x; 1.0018x over previous
; #define PG8_STAGE(bufoff, gbase, voff) do { _Pragma("unroll") for (int _i = 0; _i < 2; ++_i) \
;         __builtin_amdgcn_global_load_lds((const unsigned*)((const char*)(gbase) + (voff)[_i]), (PG8_LAS unsigned*)(lds + (bufoff) + ldsw + _i * 8192), 16, 0, 0); } while (0)
; #define PG8_LDA(dst, b, h) do { _Pragma("unroll") for (int m = 0; m < 4; ++m) _Pragma("unroll") for (int k = 0; k < 2; ++k) dst[m][k] = *(const PG8_LAS bf16x8*)(lds + PG8_SA(b, h) + aoff + m * 2048 + k * 1024); } while (0)
; #define PG8_LDB(dst, b, h) do { _Pragma("unroll") for (int n = 0; n < 2; ++n) _Pragma("unroll") for (int k = 0; k < 2; ++k) dst[n][k] = *(const PG8_LAS bf16x8*)(lds + PG8_SB(b, h) + boff + n * 2048 + k * 1024); } while (0)
; #define PG8_MMA(ai, bj, At, Bt) do { __builtin_amdgcn_s_setprio(1); _Pragma("unroll") for (int m = 0; m < 4; ++m) _Pragma("unroll") for (int n = 0; n < 2; ++n) _Pragma("unroll") for (int k = 0; k < 2; ++k) \
;         acc[ai][bj][m][n] = __builtin_amdgcn_mfma_f32_16x16x32_bf16(Bt[n][k], At[m][k], acc[ai][bj][m][n], 0, 0, 0); __builtin_amdgcn_s_setprio(0); } while (0)
; #define PG8_WAIT_V(n) asm volatile("s_waitcnt vmcnt(" #n ")" ::: "memory")
; #define PG8_WAIT_L(n) asm volatile("s_waitcnt lgkmcnt(" #n ")" ::: "memory")
; #define PG8_BAR __builtin_amdgcn_s_barrier()
; #define PG8_SCHED __builtin_amdgcn_sched_barrier(0)
; template <class Epi, class Sched, bool ALIGN_EPI = false, bool SP2 = false>
; __device__ __forceinline__ void gemm_phase(PG8_LAS unsigned char* lds, const Gemm g, const Sched& S, const Epi& E) {
;     ...
;             PG8_LDB(B0, 0, 0); PG8_LDB(B1, 0, 1); PG8_SCHED; PG8_LDA(At, 0, 0); PG8_STAGE(PG8_SA(1, 1), a1 + hstep, voffA);
;             PG8_WAIT_V(8); PG8_WAIT_L(0); PG8_BAR; PG8_MMA(0, 0, At, B0); PG8_MMA(0, 1, At, B1); PG8_BAR; PG8_SCHED;
;             PG8_LDA(At, 0, 1); PG8_STAGE(PG8_SB(0, 0), b2, voffB); PG8_STAGE(PG8_SB(0, 1), b2 + hstep, voffB); PG8_STAGE(PG8_SA(0, 0), a2, voffA);
;             PG8_WAIT_V(8); PG8_WAIT_L(0); PG8_BAR; PG8_MMA(1, 0, At, B0); PG8_MMA(1, 1, At, B1); PG8_BAR; PG8_SCHED;
.LBB11_228:
	ds_read_b128 v[152:155], v149
	ds_read_b128 v[156:159], v149 offset:1024
	ds_read_b128 v[160:163], v149 offset:2048
	ds_read_b128 v[164:167], v149 offset:3072
	ds_read_b128 v[168:171], v150
	ds_read_b128 v[172:175], v150 offset:1024
	ds_read_b128 v[176:179], v150 offset:2048
	ds_read_b128 v[180:183], v150 offset:3072
	s_add_u32 s30, s28, 0xfff80080
	s_addc_u32 s31, s29, -1
	s_cmp_eq_u32 s61, 28
	s_cselect_b32 s35, s21, s31
	s_cselect_b32 s34, s57, s30
	s_cselect_b32 s31, s19, s60
	s_cselect_b32 s30, s58, s59
	v_lshl_add_u64 v[144:145], s[28:29], 0, v[140:141]
	s_add_i32 m0, s27, 0xc000
	ds_read_b128 v[184:187], v151
	ds_read_b128 v[188:191], v151 offset:1024
	ds_read_b128 v[192:195], v151 offset:2048
	ds_read_b128 v[196:199], v151 offset:3072
	ds_read_b128 v[200:203], v151 offset:4096
	ds_read_b128 v[204:207], v151 offset:5120
	ds_read_b128 v[210:213], v151 offset:6144
	ds_read_b128 v[214:217], v151 offset:7168
	global_load_lds_dwordx4 v[144:145], off
	v_lshl_add_u64 v[144:145], s[28:29], 0, v[142:143]
	s_add_i32 m0, s27, 0xe000
	s_nop 0
	global_load_lds_dwordx4 v[144:145], off
	s_waitcnt vmcnt(8)
	s_waitcnt lgkmcnt(0)
	s_barrier
	s_setprio 1
	s_waitcnt lgkmcnt(0)
	v_mfma_f32_16x16x32_bf16 v[126:129], v[152:155], v[184:187], v[126:129]
	v_mfma_f32_16x16x32_bf16 v[126:129], v[156:159], v[188:191], v[126:129]
	v_mfma_f32_16x16x32_bf16 v[122:125], v[160:163], v[184:187], v[122:125]
	v_mfma_f32_16x16x32_bf16 v[122:125], v[164:167], v[188:191], v[122:125]
	v_mfma_f32_16x16x32_bf16 v[118:121], v[152:155], v[192:195], v[118:121]
	v_mfma_f32_16x16x32_bf16 v[118:121], v[156:159], v[196:199], v[118:121]
	v_mfma_f32_16x16x32_bf16 v[110:113], v[160:163], v[192:195], v[110:113]
	v_mfma_f32_16x16x32_bf16 v[110:113], v[164:167], v[196:199], v[110:113]
	v_mfma_f32_16x16x32_bf16 v[102:105], v[152:155], v[200:203], v[102:105]
	v_mfma_f32_16x16x32_bf16 v[102:105], v[156:159], v[204:207], v[102:105]
	v_mfma_f32_16x16x32_bf16 v[94:97], v[160:163], v[200:203], v[94:97]
	v_mfma_f32_16x16x32_bf16 v[94:97], v[164:167], v[204:207], v[94:97]
	v_mfma_f32_16x16x32_bf16 v[86:89], v[152:155], v[210:213], v[86:89]
	v_mfma_f32_16x16x32_bf16 v[86:89], v[156:159], v[214:217], v[86:89]
	v_mfma_f32_16x16x32_bf16 v[78:81], v[160:163], v[210:213], v[78:81]
	v_mfma_f32_16x16x32_bf16 v[78:81], v[164:167], v[214:217], v[78:81]
	s_setprio 0
	s_setprio 1
	v_mfma_f32_16x16x32_bf16 v[114:117], v[168:171], v[184:187], v[114:117]
	v_mfma_f32_16x16x32_bf16 v[114:117], v[172:175], v[188:191], v[114:117]
	v_mfma_f32_16x16x32_bf16 v[106:109], v[176:179], v[184:187], v[106:109]
	v_mfma_f32_16x16x32_bf16 v[106:109], v[180:183], v[188:191], v[106:109]
	v_mfma_f32_16x16x32_bf16 v[98:101], v[168:171], v[192:195], v[98:101]
	v_mfma_f32_16x16x32_bf16 v[98:101], v[172:175], v[196:199], v[98:101]
	v_mfma_f32_16x16x32_bf16 v[90:93], v[176:179], v[192:195], v[90:93]
	v_mfma_f32_16x16x32_bf16 v[90:93], v[180:183], v[196:199], v[90:93]
	v_mfma_f32_16x16x32_bf16 v[82:85], v[168:171], v[200:203], v[82:85]
	v_mfma_f32_16x16x32_bf16 v[82:85], v[172:175], v[204:207], v[82:85]
	v_mfma_f32_16x16x32_bf16 v[74:77], v[176:179], v[200:203], v[74:77]
	v_mfma_f32_16x16x32_bf16 v[74:77], v[180:183], v[204:207], v[74:77]
	v_mfma_f32_16x16x32_bf16 v[70:73], v[168:171], v[210:213], v[70:73]
	v_mfma_f32_16x16x32_bf16 v[70:73], v[172:175], v[214:217], v[70:73]
	v_mfma_f32_16x16x32_bf16 v[66:69], v[176:179], v[210:213], v[66:69]
	v_mfma_f32_16x16x32_bf16 v[66:69], v[180:183], v[214:217], v[66:69]
	s_setprio 0
	s_barrier
	s_add_i32 s62, s50, s37
	v_lshl_add_u64 v[144:145], s[30:31], 0, v[134:135]
	s_mov_b32 m0, s62
	ds_read_b128 v[184:187], v151 offset:16384
	ds_read_b128 v[188:191], v151 offset:17408
	ds_read_b128 v[192:195], v151 offset:18432
	ds_read_b128 v[196:199], v151 offset:19456
	ds_read_b128 v[200:203], v151 offset:20480
	ds_read_b128 v[204:207], v151 offset:21504
	ds_read_b128 v[210:213], v151 offset:22528
	ds_read_b128 v[214:217], v151 offset:23552
	global_load_lds_dwordx4 v[144:145], off
	s_add_i32 m0, s62, 0x2000
	s_add_u32 s62, s30, 0x80000
	v_lshl_add_u64 v[218:219], s[30:31], 0, v[130:131]
	s_addc_u32 s63, s31, 0
	s_add_i32 s64, s51, s37
	global_load_lds_dwordx4 v[218:219], off
	v_lshl_add_u64 v[220:221], s[62:63], 0, v[134:135]
	s_mov_b32 m0, s64
	v_lshl_add_u64 v[222:223], s[34:35], 0, v[132:133]
	global_load_lds_dwordx4 v[220:221], off
	v_lshl_add_u64 v[220:221], s[62:63], 0, v[130:131]
	s_add_i32 m0, s64, 0x2000
	s_nop 0
	global_load_lds_dwordx4 v[220:221], off
	v_lshl_add_u64 v[220:221], s[34:35], 0, v[136:137]
	s_mov_b32 m0, s27
	s_nop 0
	global_load_lds_dwordx4 v[220:221], off
	s_mov_b32 m0, s39
	s_nop 0
	global_load_lds_dwordx4 v[222:223], off
	s_waitcnt vmcnt(8)
	s_waitcnt lgkmcnt(0)
	s_barrier
; #define PG8_STAGE(bufoff, gbase, voff) do { _Pragma("unroll") for (int _i = 0; _i < 2; ++_i) \
;         __builtin_amdgcn_global_load_lds((const unsigned*)((const char*)(gbase) + (voff)[_i]), (PG8_LAS unsigned*)(lds + (bufoff) + ldsw + _i * 8192), 16, 0, 0); } while (0)
; #define PG8_LDA(dst, b, h) do { _Pragma("unroll") for (int m = 0; m < 4; ++m) _Pragma("unroll") for (int k = 0; k < 2; ++k) dst[m][k] = *(const PG8_LAS bf16x8*)(lds + PG8_SA(b, h) + aoff + m * 2048 + k * 1024); } while (0)
; #define PG8_LDB(dst, b, h) do { _Pragma("unroll") for (int n = 0; n < 2; ++n) _Pragma("unroll") for (int k = 0; k < 2; ++k) dst[n][k] = *(const PG8_LAS bf16x8*)(lds + PG8_SB(b, h) + boff + n * 2048 + k * 1024); } while (0)
; #define PG8_MMA(ai, bj, At, Bt) do { __builtin_amdgcn_s_setprio(1); _Pragma("unroll") for (int m = 0; m < 4; ++m) _Pragma("unroll") for (int n = 0; n < 2; ++n) _Pragma("unroll") for (int k = 0; k < 2; ++k) \
;         acc[ai][bj][m][n] = __builtin_amdgcn_mfma_f32_16x16x32_bf16(Bt[n][k], At[m][k], acc[ai][bj][m][n], 0, 0, 0); __builtin_amdgcn_s_setprio(0); } while (0)
; #define PG8_WAIT_V(n) asm volatile("s_waitcnt vmcnt(" #n ")" ::: "memory")
; #define PG8_WAIT_L(n) asm volatile("s_waitcnt lgkmcnt(" #n ")" ::: "memory")
; #define PG8_BAR __builtin_amdgcn_s_barrier()
; #define PG8_SCHED __builtin_amdgcn_sched_barrier(0)
; template <class Epi, class Sched, bool ALIGN_EPI = false, bool SP2 = false>
; __device__ __forceinline__ void gemm_phase(PG8_LAS unsigned char* lds, const Gemm g, const Sched& S, const Epi& E) {
;     ...
;             PG8_WAIT_V(8); PG8_WAIT_L(0); PG8_BAR; PG8_MMA(0, 0, At, B0); PG8_MMA(0, 1, At, B1); PG8_BAR; PG8_SCHED;
;             PG8_LDA(At, 0, 1); PG8_STAGE(PG8_SB(0, 0), b2, voffB); PG8_STAGE(PG8_SB(0, 1), b2 + hstep, voffB); PG8_STAGE(PG8_SA(0, 0), a2, voffA);
;             PG8_WAIT_V(8); PG8_WAIT_L(0); PG8_BAR; PG8_MMA(1, 0, At, B0); PG8_MMA(1, 1, At, B1); PG8_BAR; PG8_SCHED;
;             PG8_LDB(B0, 1, 0); PG8_LDB(B1, 1, 1); PG8_SCHED; PG8_LDA(At, 1, 0); PG8_STAGE(PG8_SA(0, 1), a2 + hstep, voffA);
;             PG8_WAIT_V(8); PG8_WAIT_L(0); PG8_BAR; PG8_MMA(0, 0, At, B0); PG8_MMA(0, 1, At, B1); PG8_BAR; PG8_SCHED;
	s_setprio 1
	s_waitcnt lgkmcnt(0)
	v_mfma_f32_16x16x32_bf16 v[62:65], v[152:155], v[184:187], v[62:65]
	v_mfma_f32_16x16x32_bf16 v[62:65], v[156:159], v[188:191], v[62:65]
	v_mfma_f32_16x16x32_bf16 v[58:61], v[160:163], v[184:187], v[58:61]
	v_mfma_f32_16x16x32_bf16 v[58:61], v[164:167], v[188:191], v[58:61]
	v_mfma_f32_16x16x32_bf16 v[54:57], v[152:155], v[192:195], v[54:57]
	v_mfma_f32_16x16x32_bf16 v[54:57], v[156:159], v[196:199], v[54:57]
	v_mfma_f32_16x16x32_bf16 v[46:49], v[160:163], v[192:195], v[46:49]
	v_mfma_f32_16x16x32_bf16 v[46:49], v[164:167], v[196:199], v[46:49]
	v_mfma_f32_16x16x32_bf16 v[38:41], v[152:155], v[200:203], v[38:41]
	v_mfma_f32_16x16x32_bf16 v[38:41], v[156:159], v[204:207], v[38:41]
	v_mfma_f32_16x16x32_bf16 v[30:33], v[160:163], v[200:203], v[30:33]
	v_mfma_f32_16x16x32_bf16 v[30:33], v[164:167], v[204:207], v[30:33]
	v_mfma_f32_16x16x32_bf16 v[22:25], v[152:155], v[210:213], v[22:25]
	v_mfma_f32_16x16x32_bf16 v[22:25], v[156:159], v[214:217], v[22:25]
	v_mfma_f32_16x16x32_bf16 v[14:17], v[160:163], v[210:213], v[14:17]
	v_mfma_f32_16x16x32_bf16 v[14:17], v[164:167], v[214:217], v[14:17]
	s_setprio 0
	s_setprio 1
	v_mfma_f32_16x16x32_bf16 v[50:53], v[168:171], v[184:187], v[50:53]
	v_mfma_f32_16x16x32_bf16 v[50:53], v[172:175], v[188:191], v[50:53]
	v_mfma_f32_16x16x32_bf16 v[42:45], v[176:179], v[184:187], v[42:45]
	v_mfma_f32_16x16x32_bf16 v[42:45], v[180:183], v[188:191], v[42:45]
	v_mfma_f32_16x16x32_bf16 v[34:37], v[168:171], v[192:195], v[34:37]
	v_mfma_f32_16x16x32_bf16 v[34:37], v[172:175], v[196:199], v[34:37]
	v_mfma_f32_16x16x32_bf16 v[26:29], v[176:179], v[192:195], v[26:29]
	v_mfma_f32_16x16x32_bf16 v[26:29], v[180:183], v[196:199], v[26:29]
	v_mfma_f32_16x16x32_bf16 v[18:21], v[168:171], v[200:203], v[18:21]
	v_mfma_f32_16x16x32_bf16 v[18:21], v[172:175], v[204:207], v[18:21]
	v_mfma_f32_16x16x32_bf16 v[10:13], v[176:179], v[200:203], v[10:13]
	v_mfma_f32_16x16x32_bf16 v[10:13], v[180:183], v[204:207], v[10:13]
	v_mfma_f32_16x16x32_bf16 v[6:9], v[168:171], v[210:213], v[6:9]
	v_mfma_f32_16x16x32_bf16 v[6:9], v[172:175], v[214:217], v[6:9]
	v_mfma_f32_16x16x32_bf16 v[2:5], v[176:179], v[210:213], v[2:5]
	v_mfma_f32_16x16x32_bf16 v[2:5], v[180:183], v[214:217], v[2:5]
	s_setprio 0
	s_barrier
	s_add_i32 s62, 0, 0x18000
	s_add_i32 s63, 0, 0x1c000
	v_add_u32_e32 v164, s62, v147
	v_add_u32_e32 v180, s63, v147
	ds_read_b128 v[152:155], v164
	ds_read_b128 v[156:159], v164 offset:1024
	ds_read_b128 v[160:163], v164 offset:2048
	ds_read_b128 v[164:167], v164 offset:3072
	ds_read_b128 v[168:171], v180
	ds_read_b128 v[172:175], v180 offset:1024
	ds_read_b128 v[176:179], v180 offset:2048
	ds_read_b128 v[180:183], v180 offset:3072
	s_add_u32 s34, s34, 0x80000
	s_addc_u32 s35, s35, 0
	s_mov_b32 m0, s40
	v_lshl_add_u64 v[224:225], s[34:35], 0, v[136:137]
	ds_read_b128 v[184:187], v151 offset:32768
	ds_read_b128 v[188:191], v151 offset:33792
	ds_read_b128 v[192:195], v151 offset:34816
	ds_read_b128 v[196:199], v151 offset:35840
	ds_read_b128 v[200:203], v151 offset:36864
	ds_read_b128 v[204:207], v151 offset:37888
	ds_read_b128 v[210:213], v151 offset:38912
	ds_read_b128 v[214:217], v151 offset:39936
	global_load_lds_dwordx4 v[224:225], off
	v_lshl_add_u64 v[224:225], s[34:35], 0, v[132:133]
	s_mov_b32 m0, s41
	s_nop 0
	global_load_lds_dwordx4 v[224:225], off
	s_waitcnt vmcnt(8)
	s_waitcnt lgkmcnt(0)
	s_barrier
	s_setprio 1
	s_waitcnt lgkmcnt(0)
	v_mfma_f32_16x16x32_bf16 v[126:129], v[152:155], v[184:187], v[126:129]
	v_mfma_f32_16x16x32_bf16 v[126:129], v[156:159], v[188:191], v[126:129]
	v_mfma_f32_16x16x32_bf16 v[122:125], v[160:163], v[184:187], v[122:125]
	v_mfma_f32_16x16x32_bf16 v[122:125], v[164:167], v[188:191], v[122:125]
	v_mfma_f32_16x16x32_bf16 v[118:121], v[152:155], v[192:195], v[118:121]
	v_mfma_f32_16x16x32_bf16 v[118:121], v[156:159], v[196:199], v[118:121]
	v_mfma_f32_16x16x32_bf16 v[110:113], v[160:163], v[192:195], v[110:113]
	v_mfma_f32_16x16x32_bf16 v[110:113], v[164:167], v[196:199], v[110:113]
	v_mfma_f32_16x16x32_bf16 v[102:105], v[152:155], v[200:203], v[102:105]
	v_mfma_f32_16x16x32_bf16 v[102:105], v[156:159], v[204:207], v[102:105]
	v_mfma_f32_16x16x32_bf16 v[94:97], v[160:163], v[200:203], v[94:97]
	v_mfma_f32_16x16x32_bf16 v[94:97], v[164:167], v[204:207], v[94:97]
	v_mfma_f32_16x16x32_bf16 v[86:89], v[152:155], v[210:213], v[86:89]
	v_mfma_f32_16x16x32_bf16 v[86:89], v[156:159], v[214:217], v[86:89]
	v_mfma_f32_16x16x32_bf16 v[78:81], v[160:163], v[210:213], v[78:81]
	v_mfma_f32_16x16x32_bf16 v[78:81], v[164:167], v[214:217], v[78:81]
	s_setprio 0
	s_setprio 1
	v_mfma_f32_16x16x32_bf16 v[114:117], v[168:171], v[184:187], v[114:117]
	v_mfma_f32_16x16x32_bf16 v[114:117], v[172:175], v[188:191], v[114:117]
	v_mfma_f32_16x16x32_bf16 v[106:109], v[176:179], v[184:187], v[106:109]
	v_mfma_f32_16x16x32_bf16 v[106:109], v[180:183], v[188:191], v[106:109]
	v_mfma_f32_16x16x32_bf16 v[98:101], v[168:171], v[192:195], v[98:101]
	v_mfma_f32_16x16x32_bf16 v[98:101], v[172:175], v[196:199], v[98:101]
	v_mfma_f32_16x16x32_bf16 v[90:93], v[176:179], v[192:195], v[90:93]
	v_mfma_f32_16x16x32_bf16 v[90:93], v[180:183], v[196:199], v[90:93]
	v_mfma_f32_16x16x32_bf16 v[82:85], v[168:171], v[200:203], v[82:85]
	v_mfma_f32_16x16x32_bf16 v[82:85], v[172:175], v[204:207], v[82:85]
	v_mfma_f32_16x16x32_bf16 v[74:77], v[176:179], v[200:203], v[74:77]
	v_mfma_f32_16x16x32_bf16 v[74:77], v[180:183], v[204:207], v[74:77]
	v_mfma_f32_16x16x32_bf16 v[70:73], v[168:171], v[210:213], v[70:73]
	v_mfma_f32_16x16x32_bf16 v[70:73], v[172:175], v[214:217], v[70:73]
	v_mfma_f32_16x16x32_bf16 v[66:69], v[176:179], v[210:213], v[66:69]
	v_mfma_f32_16x16x32_bf16 v[66:69], v[180:183], v[214:217], v[66:69]
	s_setprio 0
	s_barrier
; #define PG8_STAGE(bufoff, gbase, voff) do { _Pragma("unroll") for (int _i = 0; _i < 2; ++_i) \
;         __builtin_amdgcn_global_load_lds((const unsigned*)((const char*)(gbase) + (voff)[_i]), (PG8_LAS unsigned*)(lds + (bufoff) + ldsw + _i * 8192), 16, 0, 0); } while (0)
; #define PG8_LDA(dst, b, h) do { _Pragma("unroll") for (int m = 0; m < 4; ++m) _Pragma("unroll") for (int k = 0; k < 2; ++k) dst[m][k] = *(const PG8_LAS bf16x8*)(lds + PG8_SA(b, h) + aoff + m * 2048 + k * 1024); } while (0)
; #define PG8_MMA(ai, bj, At, Bt) do { __builtin_amdgcn_s_setprio(1); _Pragma("unroll") for (int m = 0; m < 4; ++m) _Pragma("unroll") for (int n = 0; n < 2; ++n) _Pragma("unroll") for (int k = 0; k < 2; ++k) \
;         acc[ai][bj][m][n] = __builtin_amdgcn_mfma_f32_16x16x32_bf16(Bt[n][k], At[m][k], acc[ai][bj][m][n], 0, 0, 0); __builtin_amdgcn_s_setprio(0); } while (0)
; #define PG8_WAIT_V(n) asm volatile("s_waitcnt vmcnt(" #n ")" ::: "memory")
; #define PG8_WAIT_L(n) asm volatile("s_waitcnt lgkmcnt(" #n ")" ::: "memory")
; #define PG8_BAR __builtin_amdgcn_s_barrier()
; #define PG8_SCHED __builtin_amdgcn_sched_barrier(0)
; template <class Epi, class Sched, bool ALIGN_EPI = false, bool SP2 = false>
; __device__ __forceinline__ void gemm_phase(PG8_LAS unsigned char* lds, const Gemm g, const Sched& S, const Epi& E) {
;     ...
;         for (int t = 0; t < nt; t += 2) {
;     ...
;             PG8_LDA(At, 1, 1); PG8_STAGE(PG8_SB(1, 0), b3, voffB); PG8_STAGE(PG8_SB(1, 1), b3 + hstep, voffB); PG8_STAGE(PG8_SA(1, 0), a3, voffA);
;             PG8_WAIT_V(8); PG8_WAIT_L(0); PG8_BAR; PG8_MMA(1, 0, At, B0); PG8_MMA(1, 1, At, B1); PG8_BAR; PG8_SCHED;
	s_add_i32 s34, s62, s37
	v_lshl_add_u64 v[144:145], v[144:145], 0, s[6:7]
	s_mov_b32 m0, s34
	ds_read_b128 v[184:187], v151 offset:49152
	ds_read_b128 v[188:191], v151 offset:50176
	ds_read_b128 v[192:195], v151 offset:51200
	ds_read_b128 v[196:199], v151 offset:52224
	ds_read_b128 v[200:203], v151 offset:53248
	ds_read_b128 v[204:207], v151 offset:54272
	ds_read_b128 v[210:213], v151 offset:55296
	ds_read_b128 v[214:217], v151 offset:56320
	global_load_lds_dwordx4 v[144:145], off
	s_add_i32 m0, s34, 0x2000
	s_add_u32 s30, s30, 0x80080
	v_lshl_add_u64 v[144:145], v[218:219], 0, s[6:7]
	s_addc_u32 s31, s31, 0
	s_add_i32 s34, s63, s37
	global_load_lds_dwordx4 v[144:145], off
	v_lshl_add_u64 v[144:145], s[30:31], 0, v[134:135]
	s_mov_b32 m0, s34
	s_nop 0
	global_load_lds_dwordx4 v[144:145], off
	v_lshl_add_u64 v[144:145], s[30:31], 0, v[130:131]
	s_add_i32 m0, s34, 0x2000
	s_nop 0
	global_load_lds_dwordx4 v[144:145], off
	v_lshl_add_u64 v[144:145], v[220:221], 0, s[6:7]
	s_mov_b32 m0, s48
	s_nop 0
	global_load_lds_dwordx4 v[144:145], off
	v_lshl_add_u64 v[144:145], v[222:223], 0, s[6:7]
	s_mov_b32 m0, s49
	s_nop 0
	global_load_lds_dwordx4 v[144:145], off
	s_waitcnt vmcnt(8)
	s_waitcnt lgkmcnt(0)
	s_barrier
	s_setprio 1
	s_waitcnt lgkmcnt(0)
	v_mfma_f32_16x16x32_bf16 v[62:65], v[152:155], v[184:187], v[62:65]
	v_mfma_f32_16x16x32_bf16 v[62:65], v[156:159], v[188:191], v[62:65]
	v_mfma_f32_16x16x32_bf16 v[58:61], v[160:163], v[184:187], v[58:61]
	v_mfma_f32_16x16x32_bf16 v[58:61], v[164:167], v[188:191], v[58:61]
	v_mfma_f32_16x16x32_bf16 v[54:57], v[152:155], v[192:195], v[54:57]
	v_mfma_f32_16x16x32_bf16 v[54:57], v[156:159], v[196:199], v[54:57]
	v_mfma_f32_16x16x32_bf16 v[46:49], v[160:163], v[192:195], v[46:49]
	v_mfma_f32_16x16x32_bf16 v[46:49], v[164:167], v[196:199], v[46:49]
	v_mfma_f32_16x16x32_bf16 v[38:41], v[152:155], v[200:203], v[38:41]
	v_mfma_f32_16x16x32_bf16 v[38:41], v[156:159], v[204:207], v[38:41]
	v_mfma_f32_16x16x32_bf16 v[30:33], v[160:163], v[200:203], v[30:33]
	v_mfma_f32_16x16x32_bf16 v[30:33], v[164:167], v[204:207], v[30:33]
	v_mfma_f32_16x16x32_bf16 v[22:25], v[152:155], v[210:213], v[22:25]
	v_mfma_f32_16x16x32_bf16 v[22:25], v[156:159], v[214:217], v[22:25]
	v_mfma_f32_16x16x32_bf16 v[14:17], v[160:163], v[210:213], v[14:17]
	v_mfma_f32_16x16x32_bf16 v[14:17], v[164:167], v[214:217], v[14:17]
	s_setprio 0
	s_setprio 1
	v_mfma_f32_16x16x32_bf16 v[50:53], v[168:171], v[184:187], v[50:53]
	v_mfma_f32_16x16x32_bf16 v[50:53], v[172:175], v[188:191], v[50:53]
	v_mfma_f32_16x16x32_bf16 v[42:45], v[176:179], v[184:187], v[42:45]
	v_mfma_f32_16x16x32_bf16 v[42:45], v[180:183], v[188:191], v[42:45]
	v_mfma_f32_16x16x32_bf16 v[34:37], v[168:171], v[192:195], v[34:37]
	v_mfma_f32_16x16x32_bf16 v[34:37], v[172:175], v[196:199], v[34:37]
	v_mfma_f32_16x16x32_bf16 v[26:29], v[176:179], v[192:195], v[26:29]
	v_mfma_f32_16x16x32_bf16 v[26:29], v[180:183], v[196:199], v[26:29]
	v_mfma_f32_16x16x32_bf16 v[18:21], v[168:171], v[200:203], v[18:21]
	v_mfma_f32_16x16x32_bf16 v[18:21], v[172:175], v[204:207], v[18:21]
	v_mfma_f32_16x16x32_bf16 v[10:13], v[176:179], v[200:203], v[10:13]
	v_mfma_f32_16x16x32_bf16 v[10:13], v[180:183], v[204:207], v[10:13]
	v_mfma_f32_16x16x32_bf16 v[6:9], v[168:171], v[210:213], v[6:9]
	v_mfma_f32_16x16x32_bf16 v[6:9], v[172:175], v[214:217], v[6:9]
	v_mfma_f32_16x16x32_bf16 v[2:5], v[176:179], v[210:213], v[2:5]
	v_mfma_f32_16x16x32_bf16 v[2:5], v[180:183], v[214:217], v[2:5]
	s_setprio 0
	s_barrier
	s_add_i32 s61, s61, 2
	s_add_u32 s28, s28, 0x100
	s_addc_u32 s29, s29, 0
	s_add_u32 s59, s59, 0x100
	s_addc_u32 s60, s60, 0
	s_cmp_gt_u32 s61, 29
	s_cbranch_scc0 .LBB11_228
	s_and_b64 vcc, exec, s[8:9]
	s_cbranch_vccz .LBB11_231
	s_barrier

; #define PG8_STAGE(bufoff, gbase, voff) do { _Pragma("unroll") for (int _i = 0; _i < 2; ++_i) \
;         __builtin_amdgcn_global_load_lds((const unsigned*)((const char*)(gbase) + (voff)[_i]), (PG8_LAS unsigned*)(lds + (bufoff) + ldsw + _i * 8192), 16, 0, 0); } while (0)
; #define PG8_LDA(dst, b, h) do { _Pragma("unroll") for (int m = 0; m < 4; ++m) _Pragma("unroll") for (int k = 0; k < 2; ++k) dst[m][k] = *(const PG8_LAS bf16x8*)(lds + PG8_SA(b, h) + aoff + m * 2048 + k * 1024); } while (0)
; #define PG8_LDB(dst, b, h) do { _Pragma("unroll") for (int n = 0; n < 2; ++n) _Pragma("unroll") for (int k = 0; k < 2; ++k) dst[n][k] = *(const PG8_LAS bf16x8*)(lds + PG8_SB(b, h) + boff + n * 2048 + k * 1024); } while (0)
; #define PG8_MMA(ai, bj, At, Bt) do { __builtin_amdgcn_s_setprio(1); _Pragma("unroll") for (int m = 0; m < 4; ++m) _Pragma("unroll") for (int n = 0; n < 2; ++n) _Pragma("unroll") for (int k = 0; k < 2; ++k) \
;         acc[ai][bj][m][n] = __builtin_amdgcn_mfma_f32_16x16x32_bf16(Bt[n][k], At[m][k], acc[ai][bj][m][n], 0, 0, 0); __builtin_amdgcn_s_setprio(0); } while (0)
; #define PG8_WAIT_V(n) asm volatile("s_waitcnt vmcnt(" #n ")" ::: "memory")
; #define PG8_WAIT_L(n) asm volatile("s_waitcnt lgkmcnt(" #n ")" ::: "memory")
; #define PG8_BAR __builtin_amdgcn_s_barrier()
; #define PG8_SCHED __builtin_amdgcn_sched_barrier(0)
; template <class Epi, class Sched, bool ALIGN_EPI = false, bool SP2 = false>
; __device__ __forceinline__ void gemm_phase(PG8_LAS unsigned char* lds, const Gemm g, const Sched& S, const Epi& E) {
;     ...
;             PG8_LDB(B0, 0, 0); PG8_LDB(B1, 0, 1); PG8_SCHED; PG8_LDA(At, 0, 0); PG8_STAGE(PG8_SA(1, 1), a1 + hstep, voffA);
;             PG8_WAIT_V(8); PG8_WAIT_L(0); PG8_BAR; PG8_MMA(0, 0, At, B0); PG8_MMA(0, 1, At, B1); PG8_BAR; PG8_SCHED;
;             PG8_LDA(At, 0, 1); PG8_STAGE(PG8_SB(0, 0), b2, voffB); PG8_STAGE(PG8_SB(0, 1), b2 + hstep, voffB); PG8_STAGE(PG8_SA(0, 0), a2, voffA);
;             PG8_WAIT_V(8); PG8_WAIT_L(0); PG8_BAR; PG8_MMA(1, 0, At, B0); PG8_MMA(1, 1, At, B1); PG8_BAR; PG8_SCHED;
.LBB11_638:
	s_add_u32 s20, s18, 0xfff80080
	s_addc_u32 s21, s19, -1
	s_add_i32 s49, 0, 0x10000
	s_cmp_eq_u32 s48, 28
	s_cselect_b32 s23, s13, s21
	s_cselect_b32 s22, s44, s20
	v_add_u32_e32 v144, s49, v147
	s_cselect_b32 s21, s11, s47
	s_cselect_b32 s20, s45, s46
	s_add_i32 s52, 0, 0x14000
	ds_read_b128 v[150:153], v144
	ds_read_b128 v[154:157], v144 offset:1024
	ds_read_b128 v[158:161], v144 offset:2048
	ds_read_b128 v[162:165], v144 offset:3072
	v_add_u32_e32 v144, s52, v147
	ds_read_b128 v[166:169], v144
	ds_read_b128 v[170:173], v144 offset:1024
	ds_read_b128 v[174:177], v144 offset:2048
	ds_read_b128 v[178:181], v144 offset:3072
	v_lshl_add_u64 v[144:145], s[18:19], 0, v[140:141]
	s_add_i32 m0, s33, 0xc000
	ds_read_b128 v[198:201], v149
	ds_read_b128 v[202:205], v149 offset:1024
	ds_read_b128 v[220:223], v149 offset:2048
	ds_read_b128 v[224:227], v149 offset:3072
	ds_read_b128 v[228:231], v149 offset:4096
	ds_read_b128 v[232:235], v149 offset:5120
	ds_read_b128 v[236:239], v149 offset:6144
	ds_read_b128 v[240:243], v149 offset:7168
	global_load_lds_dwordx4 v[144:145], off
	v_lshl_add_u64 v[144:145], s[18:19], 0, v[142:143]
	s_add_i32 m0, s33, 0xe000
	s_nop 0
	global_load_lds_dwordx4 v[144:145], off
	s_waitcnt vmcnt(8)
	s_waitcnt lgkmcnt(0)
	s_barrier
	s_setprio 1
	s_waitcnt lgkmcnt(0)
	v_mfma_f32_16x16x32_bf16 v[128:131], v[150:153], v[198:201], v[128:131]
	v_mfma_f32_16x16x32_bf16 v[128:131], v[154:157], v[202:205], v[128:131]
	v_mfma_f32_16x16x32_bf16 v[124:127], v[158:161], v[198:201], v[124:127]
	v_mfma_f32_16x16x32_bf16 v[124:127], v[162:165], v[202:205], v[124:127]
	v_mfma_f32_16x16x32_bf16 v[120:123], v[150:153], v[220:223], v[120:123]
	v_mfma_f32_16x16x32_bf16 v[120:123], v[154:157], v[224:227], v[120:123]
	v_mfma_f32_16x16x32_bf16 v[112:115], v[158:161], v[220:223], v[112:115]
	v_mfma_f32_16x16x32_bf16 v[112:115], v[162:165], v[224:227], v[112:115]
	v_mfma_f32_16x16x32_bf16 v[104:107], v[150:153], v[228:231], v[104:107]
	v_mfma_f32_16x16x32_bf16 v[104:107], v[154:157], v[232:235], v[104:107]
	v_mfma_f32_16x16x32_bf16 v[96:99], v[158:161], v[228:231], v[96:99]
	v_mfma_f32_16x16x32_bf16 v[96:99], v[162:165], v[232:235], v[96:99]
	v_mfma_f32_16x16x32_bf16 v[88:91], v[150:153], v[236:239], v[88:91]
	v_mfma_f32_16x16x32_bf16 v[88:91], v[154:157], v[240:243], v[88:91]
	v_mfma_f32_16x16x32_bf16 v[80:83], v[158:161], v[236:239], v[80:83]
	v_mfma_f32_16x16x32_bf16 v[80:83], v[162:165], v[240:243], v[80:83]
	s_setprio 0
	s_setprio 1
	v_mfma_f32_16x16x32_bf16 v[116:119], v[166:169], v[198:201], v[116:119]
	v_mfma_f32_16x16x32_bf16 v[116:119], v[170:173], v[202:205], v[116:119]
	v_mfma_f32_16x16x32_bf16 v[108:111], v[174:177], v[198:201], v[108:111]
	v_mfma_f32_16x16x32_bf16 v[108:111], v[178:181], v[202:205], v[108:111]
	v_mfma_f32_16x16x32_bf16 v[100:103], v[166:169], v[220:223], v[100:103]
	v_mfma_f32_16x16x32_bf16 v[100:103], v[170:173], v[224:227], v[100:103]
	v_mfma_f32_16x16x32_bf16 v[92:95], v[174:177], v[220:223], v[92:95]
	v_mfma_f32_16x16x32_bf16 v[92:95], v[178:181], v[224:227], v[92:95]
	v_mfma_f32_16x16x32_bf16 v[84:87], v[166:169], v[228:231], v[84:87]
	v_mfma_f32_16x16x32_bf16 v[84:87], v[170:173], v[232:235], v[84:87]
	v_mfma_f32_16x16x32_bf16 v[76:79], v[174:177], v[228:231], v[76:79]
	v_mfma_f32_16x16x32_bf16 v[76:79], v[178:181], v[232:235], v[76:79]
	v_mfma_f32_16x16x32_bf16 v[72:75], v[166:169], v[236:239], v[72:75]
	v_mfma_f32_16x16x32_bf16 v[72:75], v[170:173], v[240:243], v[72:75]
	v_mfma_f32_16x16x32_bf16 v[68:71], v[174:177], v[236:239], v[68:71]
	v_mfma_f32_16x16x32_bf16 v[68:71], v[178:181], v[240:243], v[68:71]
	s_setprio 0
	s_barrier
	s_add_i32 s49, s49, s30
	v_lshl_add_u64 v[144:145], s[20:21], 0, v[2:3]
	s_mov_b32 m0, s49
	ds_read_b128 v[198:201], v149 offset:16384
	ds_read_b128 v[202:205], v149 offset:17408
	ds_read_b128 v[220:223], v149 offset:18432
	ds_read_b128 v[224:227], v149 offset:19456
	ds_read_b128 v[228:231], v149 offset:20480
	ds_read_b128 v[232:235], v149 offset:21504
	ds_read_b128 v[236:239], v149 offset:22528
	ds_read_b128 v[240:243], v149 offset:23552
	global_load_lds_dwordx4 v[144:145], off
	s_add_i32 m0, s49, 0x2000
	s_add_u32 s50, s20, 0x80000
	v_lshl_add_u64 v[184:185], s[20:21], 0, v[132:133]
	s_addc_u32 s51, s21, 0
	s_add_i32 s49, s52, s30
	global_load_lds_dwordx4 v[184:185], off
	v_lshl_add_u64 v[186:187], s[50:51], 0, v[2:3]
	s_mov_b32 m0, s49
	v_lshl_add_u64 v[196:197], s[22:23], 0, v[134:135]
	global_load_lds_dwordx4 v[186:187], off
	v_lshl_add_u64 v[186:187], s[50:51], 0, v[132:133]
	s_add_i32 m0, s49, 0x2000
	s_nop 0
	global_load_lds_dwordx4 v[186:187], off
	v_lshl_add_u64 v[186:187], s[22:23], 0, v[136:137]
	s_mov_b32 m0, s33
	s_nop 0
	global_load_lds_dwordx4 v[186:187], off
	s_mov_b32 m0, s36
	s_nop 0
	global_load_lds_dwordx4 v[196:197], off
	s_waitcnt vmcnt(8)
	s_waitcnt lgkmcnt(0)
	s_barrier
; #define PG8_STAGE(bufoff, gbase, voff) do { _Pragma("unroll") for (int _i = 0; _i < 2; ++_i) \
;         __builtin_amdgcn_global_load_lds((const unsigned*)((const char*)(gbase) + (voff)[_i]), (PG8_LAS unsigned*)(lds + (bufoff) + ldsw + _i * 8192), 16, 0, 0); } while (0)
; #define PG8_LDA(dst, b, h) do { _Pragma("unroll") for (int m = 0; m < 4; ++m) _Pragma("unroll") for (int k = 0; k < 2; ++k) dst[m][k] = *(const PG8_LAS bf16x8*)(lds + PG8_SA(b, h) + aoff + m * 2048 + k * 1024); } while (0)
; #define PG8_LDB(dst, b, h) do { _Pragma("unroll") for (int n = 0; n < 2; ++n) _Pragma("unroll") for (int k = 0; k < 2; ++k) dst[n][k] = *(const PG8_LAS bf16x8*)(lds + PG8_SB(b, h) + boff + n * 2048 + k * 1024); } while (0)
; #define PG8_MMA(ai, bj, At, Bt) do { __builtin_amdgcn_s_setprio(1); _Pragma("unroll") for (int m = 0; m < 4; ++m) _Pragma("unroll") for (int n = 0; n < 2; ++n) _Pragma("unroll") for (int k = 0; k < 2; ++k) \
;         acc[ai][bj][m][n] = __builtin_amdgcn_mfma_f32_16x16x32_bf16(Bt[n][k], At[m][k], acc[ai][bj][m][n], 0, 0, 0); __builtin_amdgcn_s_setprio(0); } while (0)
; #define PG8_WAIT_V(n) asm volatile("s_waitcnt vmcnt(" #n ")" ::: "memory")
; #define PG8_WAIT_L(n) asm volatile("s_waitcnt lgkmcnt(" #n ")" ::: "memory")
; #define PG8_BAR __builtin_amdgcn_s_barrier()
; #define PG8_SCHED __builtin_amdgcn_sched_barrier(0)
; template <class Epi, class Sched, bool ALIGN_EPI = false, bool SP2 = false>
; __device__ __forceinline__ void gemm_phase(PG8_LAS unsigned char* lds, const Gemm g, const Sched& S, const Epi& E) {
;     ...
;             PG8_WAIT_V(8); PG8_WAIT_L(0); PG8_BAR; PG8_MMA(0, 0, At, B0); PG8_MMA(0, 1, At, B1); PG8_BAR; PG8_SCHED;
;             PG8_LDA(At, 0, 1); PG8_STAGE(PG8_SB(0, 0), b2, voffB); PG8_STAGE(PG8_SB(0, 1), b2 + hstep, voffB); PG8_STAGE(PG8_SA(0, 0), a2, voffA);
;             PG8_WAIT_V(8); PG8_WAIT_L(0); PG8_BAR; PG8_MMA(1, 0, At, B0); PG8_MMA(1, 1, At, B1); PG8_BAR; PG8_SCHED;
;             PG8_LDB(B0, 1, 0); PG8_LDB(B1, 1, 1); PG8_SCHED; PG8_LDA(At, 1, 0); PG8_STAGE(PG8_SA(0, 1), a2 + hstep, voffA);
;             PG8_WAIT_V(8); PG8_WAIT_L(0); PG8_BAR; PG8_MMA(0, 0, At, B0); PG8_MMA(0, 1, At, B1); PG8_BAR; PG8_SCHED;
	s_setprio 1
	s_waitcnt lgkmcnt(0)
	v_mfma_f32_16x16x32_bf16 v[64:67], v[150:153], v[198:201], v[64:67]
	v_mfma_f32_16x16x32_bf16 v[64:67], v[154:157], v[202:205], v[64:67]
	v_mfma_f32_16x16x32_bf16 v[60:63], v[158:161], v[198:201], v[60:63]
	v_mfma_f32_16x16x32_bf16 v[60:63], v[162:165], v[202:205], v[60:63]
	v_mfma_f32_16x16x32_bf16 v[56:59], v[150:153], v[220:223], v[56:59]
	v_mfma_f32_16x16x32_bf16 v[56:59], v[154:157], v[224:227], v[56:59]
	v_mfma_f32_16x16x32_bf16 v[48:51], v[158:161], v[220:223], v[48:51]
	v_mfma_f32_16x16x32_bf16 v[48:51], v[162:165], v[224:227], v[48:51]
	v_mfma_f32_16x16x32_bf16 v[40:43], v[150:153], v[228:231], v[40:43]
	v_mfma_f32_16x16x32_bf16 v[40:43], v[154:157], v[232:235], v[40:43]
	v_mfma_f32_16x16x32_bf16 v[32:35], v[158:161], v[228:231], v[32:35]
	v_mfma_f32_16x16x32_bf16 v[32:35], v[162:165], v[232:235], v[32:35]
	v_mfma_f32_16x16x32_bf16 v[24:27], v[150:153], v[236:239], v[24:27]
	v_mfma_f32_16x16x32_bf16 v[24:27], v[154:157], v[240:243], v[24:27]
	v_mfma_f32_16x16x32_bf16 v[16:19], v[158:161], v[236:239], v[16:19]
	v_mfma_f32_16x16x32_bf16 v[16:19], v[162:165], v[240:243], v[16:19]
	s_setprio 0
	s_setprio 1
	v_mfma_f32_16x16x32_bf16 v[52:55], v[166:169], v[198:201], v[52:55]
	v_mfma_f32_16x16x32_bf16 v[52:55], v[170:173], v[202:205], v[52:55]
	v_mfma_f32_16x16x32_bf16 v[44:47], v[174:177], v[198:201], v[44:47]
	v_mfma_f32_16x16x32_bf16 v[44:47], v[178:181], v[202:205], v[44:47]
	v_mfma_f32_16x16x32_bf16 v[36:39], v[166:169], v[220:223], v[36:39]
	v_mfma_f32_16x16x32_bf16 v[36:39], v[170:173], v[224:227], v[36:39]
	v_mfma_f32_16x16x32_bf16 v[28:31], v[174:177], v[220:223], v[28:31]
	v_mfma_f32_16x16x32_bf16 v[28:31], v[178:181], v[224:227], v[28:31]
	v_mfma_f32_16x16x32_bf16 v[20:23], v[166:169], v[228:231], v[20:23]
	v_mfma_f32_16x16x32_bf16 v[20:23], v[170:173], v[232:235], v[20:23]
	v_mfma_f32_16x16x32_bf16 v[12:15], v[174:177], v[228:231], v[12:15]
	v_mfma_f32_16x16x32_bf16 v[12:15], v[178:181], v[232:235], v[12:15]
	v_mfma_f32_16x16x32_bf16 v[8:11], v[166:169], v[236:239], v[8:11]
	v_mfma_f32_16x16x32_bf16 v[8:11], v[170:173], v[240:243], v[8:11]
	v_mfma_f32_16x16x32_bf16 v[4:7], v[174:177], v[236:239], v[4:7]
	v_mfma_f32_16x16x32_bf16 v[4:7], v[178:181], v[240:243], v[4:7]
	s_setprio 0
	s_barrier
	s_add_i32 s49, 0, 0x18000
	s_add_i32 s50, 0, 0x1c000
	v_add_u32_e32 v162, s49, v147
	v_add_u32_e32 v178, s50, v147
	ds_read_b128 v[150:153], v162
	ds_read_b128 v[154:157], v162 offset:1024
	ds_read_b128 v[158:161], v162 offset:2048
	ds_read_b128 v[162:165], v162 offset:3072
	ds_read_b128 v[166:169], v178
	ds_read_b128 v[170:173], v178 offset:1024
	ds_read_b128 v[174:177], v178 offset:2048
	ds_read_b128 v[178:181], v178 offset:3072
	s_add_u32 s22, s22, 0x80000
	s_addc_u32 s23, s23, 0
	s_mov_b32 m0, s37
	v_lshl_add_u64 v[206:207], s[22:23], 0, v[136:137]
	ds_read_b128 v[198:201], v149 offset:32768
	ds_read_b128 v[202:205], v149 offset:33792
	ds_read_b128 v[220:223], v149 offset:34816
	ds_read_b128 v[224:227], v149 offset:35840
	ds_read_b128 v[228:231], v149 offset:36864
	ds_read_b128 v[232:235], v149 offset:37888
	ds_read_b128 v[236:239], v149 offset:38912
	ds_read_b128 v[240:243], v149 offset:39936
	global_load_lds_dwordx4 v[206:207], off
	v_lshl_add_u64 v[206:207], s[22:23], 0, v[134:135]
	s_mov_b32 m0, s38
	s_nop 0
	global_load_lds_dwordx4 v[206:207], off
	s_waitcnt vmcnt(8)
	s_waitcnt lgkmcnt(0)
	s_barrier
	s_setprio 1
	s_waitcnt lgkmcnt(0)
	v_mfma_f32_16x16x32_bf16 v[128:131], v[150:153], v[198:201], v[128:131]
	v_mfma_f32_16x16x32_bf16 v[128:131], v[154:157], v[202:205], v[128:131]
	v_mfma_f32_16x16x32_bf16 v[124:127], v[158:161], v[198:201], v[124:127]
	v_mfma_f32_16x16x32_bf16 v[124:127], v[162:165], v[202:205], v[124:127]
	v_mfma_f32_16x16x32_bf16 v[120:123], v[150:153], v[220:223], v[120:123]
	v_mfma_f32_16x16x32_bf16 v[120:123], v[154:157], v[224:227], v[120:123]
	v_mfma_f32_16x16x32_bf16 v[112:115], v[158:161], v[220:223], v[112:115]
	v_mfma_f32_16x16x32_bf16 v[112:115], v[162:165], v[224:227], v[112:115]
	v_mfma_f32_16x16x32_bf16 v[104:107], v[150:153], v[228:231], v[104:107]
	v_mfma_f32_16x16x32_bf16 v[104:107], v[154:157], v[232:235], v[104:107]
	v_mfma_f32_16x16x32_bf16 v[96:99], v[158:161], v[228:231], v[96:99]
	v_mfma_f32_16x16x32_bf16 v[96:99], v[162:165], v[232:235], v[96:99]
	v_mfma_f32_16x16x32_bf16 v[88:91], v[150:153], v[236:239], v[88:91]
	v_mfma_f32_16x16x32_bf16 v[88:91], v[154:157], v[240:243], v[88:91]
	v_mfma_f32_16x16x32_bf16 v[80:83], v[158:161], v[236:239], v[80:83]
	v_mfma_f32_16x16x32_bf16 v[80:83], v[162:165], v[240:243], v[80:83]
	s_setprio 0
	s_setprio 1
	v_mfma_f32_16x16x32_bf16 v[116:119], v[166:169], v[198:201], v[116:119]
	v_mfma_f32_16x16x32_bf16 v[116:119], v[170:173], v[202:205], v[116:119]
	v_mfma_f32_16x16x32_bf16 v[108:111], v[174:177], v[198:201], v[108:111]
	v_mfma_f32_16x16x32_bf16 v[108:111], v[178:181], v[202:205], v[108:111]
	v_mfma_f32_16x16x32_bf16 v[100:103], v[166:169], v[220:223], v[100:103]
	v_mfma_f32_16x16x32_bf16 v[100:103], v[170:173], v[224:227], v[100:103]
	v_mfma_f32_16x16x32_bf16 v[92:95], v[174:177], v[220:223], v[92:95]
	v_mfma_f32_16x16x32_bf16 v[92:95], v[178:181], v[224:227], v[92:95]
	v_mfma_f32_16x16x32_bf16 v[84:87], v[166:169], v[228:231], v[84:87]
	v_mfma_f32_16x16x32_bf16 v[84:87], v[170:173], v[232:235], v[84:87]
	v_mfma_f32_16x16x32_bf16 v[76:79], v[174:177], v[228:231], v[76:79]
	v_mfma_f32_16x16x32_bf16 v[76:79], v[178:181], v[232:235], v[76:79]
	v_mfma_f32_16x16x32_bf16 v[72:75], v[166:169], v[236:239], v[72:75]
	v_mfma_f32_16x16x32_bf16 v[72:75], v[170:173], v[240:243], v[72:75]
	v_mfma_f32_16x16x32_bf16 v[68:71], v[174:177], v[236:239], v[68:71]
	v_mfma_f32_16x16x32_bf16 v[68:71], v[178:181], v[240:243], v[68:71]
	s_setprio 0
	s_barrier
; #define PG8_STAGE(bufoff, gbase, voff) do { _Pragma("unroll") for (int _i = 0; _i < 2; ++_i) \
;         __builtin_amdgcn_global_load_lds((const unsigned*)((const char*)(gbase) + (voff)[_i]), (PG8_LAS unsigned*)(lds + (bufoff) + ldsw + _i * 8192), 16, 0, 0); } while (0)
; #define PG8_LDA(dst, b, h) do { _Pragma("unroll") for (int m = 0; m < 4; ++m) _Pragma("unroll") for (int k = 0; k < 2; ++k) dst[m][k] = *(const PG8_LAS bf16x8*)(lds + PG8_SA(b, h) + aoff + m * 2048 + k * 1024); } while (0)
; #define PG8_MMA(ai, bj, At, Bt) do { __builtin_amdgcn_s_setprio(1); _Pragma("unroll") for (int m = 0; m < 4; ++m) _Pragma("unroll") for (int n = 0; n < 2; ++n) _Pragma("unroll") for (int k = 0; k < 2; ++k) \
;         acc[ai][bj][m][n] = __builtin_amdgcn_mfma_f32_16x16x32_bf16(Bt[n][k], At[m][k], acc[ai][bj][m][n], 0, 0, 0); __builtin_amdgcn_s_setprio(0); } while (0)
; #define PG8_WAIT_V(n) asm volatile("s_waitcnt vmcnt(" #n ")" ::: "memory")
; #define PG8_WAIT_L(n) asm volatile("s_waitcnt lgkmcnt(" #n ")" ::: "memory")
; #define PG8_BAR __builtin_amdgcn_s_barrier()
; #define PG8_SCHED __builtin_amdgcn_sched_barrier(0)
; template <class Epi, class Sched, bool ALIGN_EPI = false, bool SP2 = false>
; __device__ __forceinline__ void gemm_phase(PG8_LAS unsigned char* lds, const Gemm g, const Sched& S, const Epi& E) {
;     ...
;         for (int t = 0; t < nt; t += 2) {
;     ...
;             PG8_LDA(At, 1, 1); PG8_STAGE(PG8_SB(1, 0), b3, voffB); PG8_STAGE(PG8_SB(1, 1), b3 + hstep, voffB); PG8_STAGE(PG8_SA(1, 0), a3, voffA);
;             PG8_WAIT_V(8); PG8_WAIT_L(0); PG8_BAR; PG8_MMA(1, 0, At, B0); PG8_MMA(1, 1, At, B1); PG8_BAR; PG8_SCHED;
	s_add_i32 s22, s49, s30
	v_lshl_add_u64 v[144:145], v[144:145], 0, s[34:35]
	s_mov_b32 m0, s22
	ds_read_b128 v[198:201], v149 offset:49152
	ds_read_b128 v[202:205], v149 offset:50176
	ds_read_b128 v[220:223], v149 offset:51200
	ds_read_b128 v[224:227], v149 offset:52224
	ds_read_b128 v[228:231], v149 offset:53248
	ds_read_b128 v[232:235], v149 offset:54272
	ds_read_b128 v[236:239], v149 offset:55296
	ds_read_b128 v[240:243], v149 offset:56320
	global_load_lds_dwordx4 v[144:145], off
	s_add_i32 m0, s22, 0x2000
	s_add_u32 s20, s20, 0x80080
	v_lshl_add_u64 v[144:145], v[184:185], 0, s[34:35]
	s_addc_u32 s21, s21, 0
	s_add_i32 s22, s50, s30
	global_load_lds_dwordx4 v[144:145], off
	v_lshl_add_u64 v[144:145], s[20:21], 0, v[2:3]
	s_mov_b32 m0, s22
	s_nop 0
	global_load_lds_dwordx4 v[144:145], off
	v_lshl_add_u64 v[144:145], s[20:21], 0, v[132:133]
	s_add_i32 m0, s22, 0x2000
	s_nop 0
	global_load_lds_dwordx4 v[144:145], off
	v_lshl_add_u64 v[144:145], v[186:187], 0, s[34:35]
	s_mov_b32 m0, s39
	s_nop 0
	global_load_lds_dwordx4 v[144:145], off
	v_lshl_add_u64 v[144:145], v[196:197], 0, s[34:35]
	s_mov_b32 m0, s40
	s_nop 0
	global_load_lds_dwordx4 v[144:145], off
	s_waitcnt vmcnt(8)
	s_waitcnt lgkmcnt(0)
	s_barrier
	s_setprio 1
	s_waitcnt lgkmcnt(0)
	v_mfma_f32_16x16x32_bf16 v[64:67], v[150:153], v[198:201], v[64:67]
	v_mfma_f32_16x16x32_bf16 v[64:67], v[154:157], v[202:205], v[64:67]
	v_mfma_f32_16x16x32_bf16 v[60:63], v[158:161], v[198:201], v[60:63]
	v_mfma_f32_16x16x32_bf16 v[60:63], v[162:165], v[202:205], v[60:63]
	v_mfma_f32_16x16x32_bf16 v[56:59], v[150:153], v[220:223], v[56:59]
	v_mfma_f32_16x16x32_bf16 v[56:59], v[154:157], v[224:227], v[56:59]
	v_mfma_f32_16x16x32_bf16 v[48:51], v[158:161], v[220:223], v[48:51]
	v_mfma_f32_16x16x32_bf16 v[48:51], v[162:165], v[224:227], v[48:51]
	v_mfma_f32_16x16x32_bf16 v[40:43], v[150:153], v[228:231], v[40:43]
	v_mfma_f32_16x16x32_bf16 v[40:43], v[154:157], v[232:235], v[40:43]
	v_mfma_f32_16x16x32_bf16 v[32:35], v[158:161], v[228:231], v[32:35]
	v_mfma_f32_16x16x32_bf16 v[32:35], v[162:165], v[232:235], v[32:35]
	v_mfma_f32_16x16x32_bf16 v[24:27], v[150:153], v[236:239], v[24:27]
	v_mfma_f32_16x16x32_bf16 v[24:27], v[154:157], v[240:243], v[24:27]
	v_mfma_f32_16x16x32_bf16 v[16:19], v[158:161], v[236:239], v[16:19]
	v_mfma_f32_16x16x32_bf16 v[16:19], v[162:165], v[240:243], v[16:19]
	s_setprio 0
	s_setprio 1
	v_mfma_f32_16x16x32_bf16 v[52:55], v[166:169], v[198:201], v[52:55]
	v_mfma_f32_16x16x32_bf16 v[52:55], v[170:173], v[202:205], v[52:55]
	v_mfma_f32_16x16x32_bf16 v[44:47], v[174:177], v[198:201], v[44:47]
	v_mfma_f32_16x16x32_bf16 v[44:47], v[178:181], v[202:205], v[44:47]
	v_mfma_f32_16x16x32_bf16 v[36:39], v[166:169], v[220:223], v[36:39]
	v_mfma_f32_16x16x32_bf16 v[36:39], v[170:173], v[224:227], v[36:39]
	v_mfma_f32_16x16x32_bf16 v[28:31], v[174:177], v[220:223], v[28:31]
	v_mfma_f32_16x16x32_bf16 v[28:31], v[178:181], v[224:227], v[28:31]
	v_mfma_f32_16x16x32_bf16 v[20:23], v[166:169], v[228:231], v[20:23]
	v_mfma_f32_16x16x32_bf16 v[20:23], v[170:173], v[232:235], v[20:23]
	v_mfma_f32_16x16x32_bf16 v[12:15], v[174:177], v[228:231], v[12:15]
	v_mfma_f32_16x16x32_bf16 v[12:15], v[178:181], v[232:235], v[12:15]
	v_mfma_f32_16x16x32_bf16 v[8:11], v[166:169], v[236:239], v[8:11]
	v_mfma_f32_16x16x32_bf16 v[8:11], v[170:173], v[240:243], v[8:11]
	v_mfma_f32_16x16x32_bf16 v[4:7], v[174:177], v[236:239], v[4:7]
	v_mfma_f32_16x16x32_bf16 v[4:7], v[178:181], v[240:243], v[4:7]
	s_setprio 0
	s_barrier
	s_add_i32 s48, s48, 2
	s_add_u32 s18, s18, 0x100
	s_addc_u32 s19, s19, 0
	s_add_u32 s46, s46, 0x100
	s_addc_u32 s47, s47, 0
	s_cmp_gt_u32 s48, 29
	s_cbranch_scc0 .LBB11_638
	s_and_b64 vcc, exec, s[4:5]
	s_cbranch_vccz .LBB11_641
	s_barrier

; #define PG8_STAGE(bufoff, gbase, voff) do { _Pragma("unroll") for (int _i = 0; _i < 2; ++_i) \
;         __builtin_amdgcn_global_load_lds((const unsigned*)((const char*)(gbase) + (voff)[_i]), (PG8_LAS unsigned*)(lds + (bufoff) + ldsw + _i * 8192), 16, 0, 0); } while (0)
; #define PG8_LDA(dst, b, h) do { _Pragma("unroll") for (int m = 0; m < 4; ++m) _Pragma("unroll") for (int k = 0; k < 2; ++k) dst[m][k] = *(const PG8_LAS bf16x8*)(lds + PG8_SA(b, h) + aoff + m * 2048 + k * 1024); } while (0)
; #define PG8_LDB(dst, b, h) do { _Pragma("unroll") for (int n = 0; n < 2; ++n) _Pragma("unroll") for (int k = 0; k < 2; ++k) dst[n][k] = *(const PG8_LAS bf16x8*)(lds + PG8_SB(b, h) + boff + n * 2048 + k * 1024); } while (0)
; #define PG8_MMA(ai, bj, At, Bt) do { __builtin_amdgcn_s_setprio(1); _Pragma("unroll") for (int m = 0; m < 4; ++m) _Pragma("unroll") for (int n = 0; n < 2; ++n) _Pragma("unroll") for (int k = 0; k < 2; ++k) \
;         acc[ai][bj][m][n] = __builtin_amdgcn_mfma_f32_16x16x32_bf16(Bt[n][k], At[m][k], acc[ai][bj][m][n], 0, 0, 0); __builtin_amdgcn_s_setprio(0); } while (0)
; #define PG8_WAIT_V(n) asm volatile("s_waitcnt vmcnt(" #n ")" ::: "memory")
; #define PG8_WAIT_L(n) asm volatile("s_waitcnt lgkmcnt(" #n ")" ::: "memory")
; #define PG8_BAR __builtin_amdgcn_s_barrier()
; #define PG8_SCHED __builtin_amdgcn_sched_barrier(0)
; template <class Epi, class Sched, bool ALIGN_EPI = false, bool SP2 = false>
; __device__ __forceinline__ void gemm_phase(PG8_LAS unsigned char* lds, const Gemm g, const Sched& S, const Epi& E) {
;     ...
;             PG8_LDB(B0, 0, 0); PG8_LDB(B1, 0, 1); PG8_SCHED; PG8_LDA(At, 0, 0); PG8_STAGE(PG8_SA(1, 1), a1 + hstep, voffA);
;             PG8_WAIT_V(8); PG8_WAIT_L(0); PG8_BAR; PG8_MMA(0, 0, At, B0); PG8_MMA(0, 1, At, B1); PG8_BAR; PG8_SCHED;
;             PG8_LDA(At, 0, 1); PG8_STAGE(PG8_SB(0, 0), b2, voffB); PG8_STAGE(PG8_SB(0, 1), b2 + hstep, voffB); PG8_STAGE(PG8_SA(0, 0), a2, voffA);
;             PG8_WAIT_V(8); PG8_WAIT_L(0); PG8_BAR; PG8_MMA(1, 0, At, B0); PG8_MMA(1, 1, At, B1); PG8_BAR; PG8_SCHED;
.LBB11_913:
	s_add_u32 s16, s14, 0xfff80080
	s_addc_u32 s17, s15, -1
	s_add_i32 s44, 0, 0x10000
	s_cmp_eq_u32 s43, 28
	s_cselect_b32 s19, s9, s17
	s_cselect_b32 s18, s37, s16
	v_add_u32_e32 v144, s44, v146
	s_cselect_b32 s17, s7, s42
	s_cselect_b32 s16, s40, s41
	s_add_i32 s46, 0, 0x14000
	ds_read_b128 v[150:153], v144
	ds_read_b128 v[154:157], v144 offset:1024
	ds_read_b128 v[158:161], v144 offset:2048
	ds_read_b128 v[162:165], v144 offset:3072
	v_add_u32_e32 v144, s46, v146
	ds_read_b128 v[166:169], v144
	ds_read_b128 v[170:173], v144 offset:1024
	ds_read_b128 v[174:177], v144 offset:2048
	ds_read_b128 v[178:181], v144 offset:3072
	v_lshl_add_u64 v[144:145], s[14:15], 0, v[140:141]
	s_add_i32 m0, s24, 0xc000
	ds_read_b128 v[198:201], v148
	ds_read_b128 v[202:205], v148 offset:1024
	ds_read_b128 v[220:223], v148 offset:2048
	ds_read_b128 v[224:227], v148 offset:3072
	ds_read_b128 v[228:231], v148 offset:4096
	ds_read_b128 v[232:235], v148 offset:5120
	ds_read_b128 v[236:239], v148 offset:6144
	ds_read_b128 v[240:243], v148 offset:7168
	global_load_lds_dwordx4 v[144:145], off
	v_lshl_add_u64 v[144:145], s[14:15], 0, v[142:143]
	s_add_i32 m0, s24, 0xe000
	s_nop 0
	global_load_lds_dwordx4 v[144:145], off
	s_waitcnt vmcnt(8)
	s_waitcnt lgkmcnt(0)
	s_barrier
	s_setprio 1
	s_waitcnt lgkmcnt(0)
	v_mfma_f32_16x16x32_bf16 v[128:131], v[150:153], v[198:201], v[128:131]
	v_mfma_f32_16x16x32_bf16 v[128:131], v[154:157], v[202:205], v[128:131]
	v_mfma_f32_16x16x32_bf16 v[124:127], v[158:161], v[198:201], v[124:127]
	v_mfma_f32_16x16x32_bf16 v[124:127], v[162:165], v[202:205], v[124:127]
	v_mfma_f32_16x16x32_bf16 v[120:123], v[150:153], v[220:223], v[120:123]
	v_mfma_f32_16x16x32_bf16 v[120:123], v[154:157], v[224:227], v[120:123]
	v_mfma_f32_16x16x32_bf16 v[112:115], v[158:161], v[220:223], v[112:115]
	v_mfma_f32_16x16x32_bf16 v[112:115], v[162:165], v[224:227], v[112:115]
	v_mfma_f32_16x16x32_bf16 v[104:107], v[150:153], v[228:231], v[104:107]
	v_mfma_f32_16x16x32_bf16 v[104:107], v[154:157], v[232:235], v[104:107]
	v_mfma_f32_16x16x32_bf16 v[96:99], v[158:161], v[228:231], v[96:99]
	v_mfma_f32_16x16x32_bf16 v[96:99], v[162:165], v[232:235], v[96:99]
	v_mfma_f32_16x16x32_bf16 v[88:91], v[150:153], v[236:239], v[88:91]
	v_mfma_f32_16x16x32_bf16 v[88:91], v[154:157], v[240:243], v[88:91]
	v_mfma_f32_16x16x32_bf16 v[80:83], v[158:161], v[236:239], v[80:83]
	v_mfma_f32_16x16x32_bf16 v[80:83], v[162:165], v[240:243], v[80:83]
	s_setprio 0
	s_setprio 1
	v_mfma_f32_16x16x32_bf16 v[116:119], v[166:169], v[198:201], v[116:119]
	v_mfma_f32_16x16x32_bf16 v[116:119], v[170:173], v[202:205], v[116:119]
	v_mfma_f32_16x16x32_bf16 v[108:111], v[174:177], v[198:201], v[108:111]
	v_mfma_f32_16x16x32_bf16 v[108:111], v[178:181], v[202:205], v[108:111]
	v_mfma_f32_16x16x32_bf16 v[100:103], v[166:169], v[220:223], v[100:103]
	v_mfma_f32_16x16x32_bf16 v[100:103], v[170:173], v[224:227], v[100:103]
	v_mfma_f32_16x16x32_bf16 v[92:95], v[174:177], v[220:223], v[92:95]
	v_mfma_f32_16x16x32_bf16 v[92:95], v[178:181], v[224:227], v[92:95]
	v_mfma_f32_16x16x32_bf16 v[84:87], v[166:169], v[228:231], v[84:87]
	v_mfma_f32_16x16x32_bf16 v[84:87], v[170:173], v[232:235], v[84:87]
	v_mfma_f32_16x16x32_bf16 v[76:79], v[174:177], v[228:231], v[76:79]
	v_mfma_f32_16x16x32_bf16 v[76:79], v[178:181], v[232:235], v[76:79]
	v_mfma_f32_16x16x32_bf16 v[72:75], v[166:169], v[236:239], v[72:75]
	v_mfma_f32_16x16x32_bf16 v[72:75], v[170:173], v[240:243], v[72:75]
	v_mfma_f32_16x16x32_bf16 v[68:71], v[174:177], v[236:239], v[68:71]
	v_mfma_f32_16x16x32_bf16 v[68:71], v[178:181], v[240:243], v[68:71]
	s_setprio 0
	s_barrier
	s_add_i32 s44, s44, s23
	v_lshl_add_u64 v[144:145], s[16:17], 0, v[2:3]
	s_mov_b32 m0, s44
	ds_read_b128 v[198:201], v148 offset:16384
	ds_read_b128 v[202:205], v148 offset:17408
	ds_read_b128 v[220:223], v148 offset:18432
	ds_read_b128 v[224:227], v148 offset:19456
	ds_read_b128 v[228:231], v148 offset:20480
	ds_read_b128 v[232:235], v148 offset:21504
	ds_read_b128 v[236:239], v148 offset:22528
	ds_read_b128 v[240:243], v148 offset:23552
	global_load_lds_dwordx4 v[144:145], off
	s_add_i32 m0, s44, 0x2000
	s_add_u32 s44, s16, 0x80000
	v_lshl_add_u64 v[184:185], s[16:17], 0, v[132:133]
	s_addc_u32 s45, s17, 0
	s_add_i32 s46, s46, s23
	global_load_lds_dwordx4 v[184:185], off
	v_lshl_add_u64 v[186:187], s[44:45], 0, v[2:3]
	s_mov_b32 m0, s46
	v_lshl_add_u64 v[196:197], s[18:19], 0, v[134:135]
	global_load_lds_dwordx4 v[186:187], off
	v_lshl_add_u64 v[186:187], s[44:45], 0, v[132:133]
	s_add_i32 m0, s46, 0x2000
	s_nop 0
	global_load_lds_dwordx4 v[186:187], off
	v_lshl_add_u64 v[186:187], s[18:19], 0, v[136:137]
	s_mov_b32 m0, s24
	s_nop 0
	global_load_lds_dwordx4 v[186:187], off
	s_mov_b32 m0, s25
	s_nop 0
	global_load_lds_dwordx4 v[196:197], off
	s_waitcnt vmcnt(8)
	s_waitcnt lgkmcnt(0)
	s_barrier
; #define PG8_STAGE(bufoff, gbase, voff) do { _Pragma("unroll") for (int _i = 0; _i < 2; ++_i) \
;         __builtin_amdgcn_global_load_lds((const unsigned*)((const char*)(gbase) + (voff)[_i]), (PG8_LAS unsigned*)(lds + (bufoff) + ldsw + _i * 8192), 16, 0, 0); } while (0)
; #define PG8_LDA(dst, b, h) do { _Pragma("unroll") for (int m = 0; m < 4; ++m) _Pragma("unroll") for (int k = 0; k < 2; ++k) dst[m][k] = *(const PG8_LAS bf16x8*)(lds + PG8_SA(b, h) + aoff + m * 2048 + k * 1024); } while (0)
; #define PG8_LDB(dst, b, h) do { _Pragma("unroll") for (int n = 0; n < 2; ++n) _Pragma("unroll") for (int k = 0; k < 2; ++k) dst[n][k] = *(const PG8_LAS bf16x8*)(lds + PG8_SB(b, h) + boff + n * 2048 + k * 1024); } while (0)
; #define PG8_MMA(ai, bj, At, Bt) do { __builtin_amdgcn_s_setprio(1); _Pragma("unroll") for (int m = 0; m < 4; ++m) _Pragma("unroll") for (int n = 0; n < 2; ++n) _Pragma("unroll") for (int k = 0; k < 2; ++k) \
;         acc[ai][bj][m][n] = __builtin_amdgcn_mfma_f32_16x16x32_bf16(Bt[n][k], At[m][k], acc[ai][bj][m][n], 0, 0, 0); __builtin_amdgcn_s_setprio(0); } while (0)
; #define PG8_WAIT_V(n) asm volatile("s_waitcnt vmcnt(" #n ")" ::: "memory")
; #define PG8_WAIT_L(n) asm volatile("s_waitcnt lgkmcnt(" #n ")" ::: "memory")
; #define PG8_BAR __builtin_amdgcn_s_barrier()
; #define PG8_SCHED __builtin_amdgcn_sched_barrier(0)
; template <class Epi, class Sched, bool ALIGN_EPI = false, bool SP2 = false>
; __device__ __forceinline__ void gemm_phase(PG8_LAS unsigned char* lds, const Gemm g, const Sched& S, const Epi& E) {
;     ...
;             PG8_WAIT_V(8); PG8_WAIT_L(0); PG8_BAR; PG8_MMA(0, 0, At, B0); PG8_MMA(0, 1, At, B1); PG8_BAR; PG8_SCHED;
;             PG8_LDA(At, 0, 1); PG8_STAGE(PG8_SB(0, 0), b2, voffB); PG8_STAGE(PG8_SB(0, 1), b2 + hstep, voffB); PG8_STAGE(PG8_SA(0, 0), a2, voffA);
;             PG8_WAIT_V(8); PG8_WAIT_L(0); PG8_BAR; PG8_MMA(1, 0, At, B0); PG8_MMA(1, 1, At, B1); PG8_BAR; PG8_SCHED;
;             PG8_LDB(B0, 1, 0); PG8_LDB(B1, 1, 1); PG8_SCHED; PG8_LDA(At, 1, 0); PG8_STAGE(PG8_SA(0, 1), a2 + hstep, voffA);
;             PG8_WAIT_V(8); PG8_WAIT_L(0); PG8_BAR; PG8_MMA(0, 0, At, B0); PG8_MMA(0, 1, At, B1); PG8_BAR; PG8_SCHED;
	s_setprio 1
	s_waitcnt lgkmcnt(0)
	v_mfma_f32_16x16x32_bf16 v[64:67], v[150:153], v[198:201], v[64:67]
	v_mfma_f32_16x16x32_bf16 v[64:67], v[154:157], v[202:205], v[64:67]
	v_mfma_f32_16x16x32_bf16 v[60:63], v[158:161], v[198:201], v[60:63]
	v_mfma_f32_16x16x32_bf16 v[60:63], v[162:165], v[202:205], v[60:63]
	v_mfma_f32_16x16x32_bf16 v[56:59], v[150:153], v[220:223], v[56:59]
	v_mfma_f32_16x16x32_bf16 v[56:59], v[154:157], v[224:227], v[56:59]
	v_mfma_f32_16x16x32_bf16 v[48:51], v[158:161], v[220:223], v[48:51]
	v_mfma_f32_16x16x32_bf16 v[48:51], v[162:165], v[224:227], v[48:51]
	v_mfma_f32_16x16x32_bf16 v[40:43], v[150:153], v[228:231], v[40:43]
	v_mfma_f32_16x16x32_bf16 v[40:43], v[154:157], v[232:235], v[40:43]
	v_mfma_f32_16x16x32_bf16 v[32:35], v[158:161], v[228:231], v[32:35]
	v_mfma_f32_16x16x32_bf16 v[32:35], v[162:165], v[232:235], v[32:35]
	v_mfma_f32_16x16x32_bf16 v[24:27], v[150:153], v[236:239], v[24:27]
	v_mfma_f32_16x16x32_bf16 v[24:27], v[154:157], v[240:243], v[24:27]
	v_mfma_f32_16x16x32_bf16 v[16:19], v[158:161], v[236:239], v[16:19]
	v_mfma_f32_16x16x32_bf16 v[16:19], v[162:165], v[240:243], v[16:19]
	s_setprio 0
	s_setprio 1
	v_mfma_f32_16x16x32_bf16 v[52:55], v[166:169], v[198:201], v[52:55]
	v_mfma_f32_16x16x32_bf16 v[52:55], v[170:173], v[202:205], v[52:55]
	v_mfma_f32_16x16x32_bf16 v[44:47], v[174:177], v[198:201], v[44:47]
	v_mfma_f32_16x16x32_bf16 v[44:47], v[178:181], v[202:205], v[44:47]
	v_mfma_f32_16x16x32_bf16 v[36:39], v[166:169], v[220:223], v[36:39]
	v_mfma_f32_16x16x32_bf16 v[36:39], v[170:173], v[224:227], v[36:39]
	v_mfma_f32_16x16x32_bf16 v[28:31], v[174:177], v[220:223], v[28:31]
	v_mfma_f32_16x16x32_bf16 v[28:31], v[178:181], v[224:227], v[28:31]
	v_mfma_f32_16x16x32_bf16 v[20:23], v[166:169], v[228:231], v[20:23]
	v_mfma_f32_16x16x32_bf16 v[20:23], v[170:173], v[232:235], v[20:23]
	v_mfma_f32_16x16x32_bf16 v[12:15], v[174:177], v[228:231], v[12:15]
	v_mfma_f32_16x16x32_bf16 v[12:15], v[178:181], v[232:235], v[12:15]
	v_mfma_f32_16x16x32_bf16 v[8:11], v[166:169], v[236:239], v[8:11]
	v_mfma_f32_16x16x32_bf16 v[8:11], v[170:173], v[240:243], v[8:11]
	v_mfma_f32_16x16x32_bf16 v[4:7], v[174:177], v[236:239], v[4:7]
	v_mfma_f32_16x16x32_bf16 v[4:7], v[178:181], v[240:243], v[4:7]
	s_setprio 0
	s_barrier
	s_add_i32 s44, 0, 0x18000
	v_add_u32_e32 v149, s44, v146
	s_add_i32 s45, 0, 0x1c000
	ds_read_b128 v[150:153], v149
	ds_read_b128 v[154:157], v149 offset:1024
	ds_read_b128 v[158:161], v149 offset:2048
	ds_read_b128 v[162:165], v149 offset:3072
	v_add_u32_e32 v149, s45, v146
	ds_read_b128 v[166:169], v149
	ds_read_b128 v[170:173], v149 offset:1024
	ds_read_b128 v[174:177], v149 offset:2048
	ds_read_b128 v[178:181], v149 offset:3072
	s_add_u32 s18, s18, 0x80000
	s_addc_u32 s19, s19, 0
	s_mov_b32 m0, s26
	v_lshl_add_u64 v[206:207], s[18:19], 0, v[136:137]
	ds_read_b128 v[198:201], v148 offset:32768
	ds_read_b128 v[202:205], v148 offset:33792
	ds_read_b128 v[220:223], v148 offset:34816
	ds_read_b128 v[224:227], v148 offset:35840
	ds_read_b128 v[228:231], v148 offset:36864
	ds_read_b128 v[232:235], v148 offset:37888
	ds_read_b128 v[236:239], v148 offset:38912
	ds_read_b128 v[240:243], v148 offset:39936
	global_load_lds_dwordx4 v[206:207], off
	v_lshl_add_u64 v[206:207], s[18:19], 0, v[134:135]
	s_mov_b32 m0, s27
	s_nop 0
	global_load_lds_dwordx4 v[206:207], off
	s_waitcnt vmcnt(8)
	s_waitcnt lgkmcnt(0)
	s_barrier
	s_setprio 1
	s_waitcnt lgkmcnt(0)
	v_mfma_f32_16x16x32_bf16 v[128:131], v[150:153], v[198:201], v[128:131]
	v_mfma_f32_16x16x32_bf16 v[128:131], v[154:157], v[202:205], v[128:131]
	v_mfma_f32_16x16x32_bf16 v[124:127], v[158:161], v[198:201], v[124:127]
	v_mfma_f32_16x16x32_bf16 v[124:127], v[162:165], v[202:205], v[124:127]
	v_mfma_f32_16x16x32_bf16 v[120:123], v[150:153], v[220:223], v[120:123]
	v_mfma_f32_16x16x32_bf16 v[120:123], v[154:157], v[224:227], v[120:123]
	v_mfma_f32_16x16x32_bf16 v[112:115], v[158:161], v[220:223], v[112:115]
	v_mfma_f32_16x16x32_bf16 v[112:115], v[162:165], v[224:227], v[112:115]
	v_mfma_f32_16x16x32_bf16 v[104:107], v[150:153], v[228:231], v[104:107]
	v_mfma_f32_16x16x32_bf16 v[104:107], v[154:157], v[232:235], v[104:107]
	v_mfma_f32_16x16x32_bf16 v[96:99], v[158:161], v[228:231], v[96:99]
	v_mfma_f32_16x16x32_bf16 v[96:99], v[162:165], v[232:235], v[96:99]
	v_mfma_f32_16x16x32_bf16 v[88:91], v[150:153], v[236:239], v[88:91]
	v_mfma_f32_16x16x32_bf16 v[88:91], v[154:157], v[240:243], v[88:91]
	v_mfma_f32_16x16x32_bf16 v[80:83], v[158:161], v[236:239], v[80:83]
	v_mfma_f32_16x16x32_bf16 v[80:83], v[162:165], v[240:243], v[80:83]
	s_setprio 0
	s_setprio 1
	v_mfma_f32_16x16x32_bf16 v[116:119], v[166:169], v[198:201], v[116:119]
	v_mfma_f32_16x16x32_bf16 v[116:119], v[170:173], v[202:205], v[116:119]
	v_mfma_f32_16x16x32_bf16 v[108:111], v[174:177], v[198:201], v[108:111]
	v_mfma_f32_16x16x32_bf16 v[108:111], v[178:181], v[202:205], v[108:111]
	v_mfma_f32_16x16x32_bf16 v[100:103], v[166:169], v[220:223], v[100:103]
	v_mfma_f32_16x16x32_bf16 v[100:103], v[170:173], v[224:227], v[100:103]
	v_mfma_f32_16x16x32_bf16 v[92:95], v[174:177], v[220:223], v[92:95]
	v_mfma_f32_16x16x32_bf16 v[92:95], v[178:181], v[224:227], v[92:95]
	v_mfma_f32_16x16x32_bf16 v[84:87], v[166:169], v[228:231], v[84:87]
	v_mfma_f32_16x16x32_bf16 v[84:87], v[170:173], v[232:235], v[84:87]
	v_mfma_f32_16x16x32_bf16 v[76:79], v[174:177], v[228:231], v[76:79]
	v_mfma_f32_16x16x32_bf16 v[76:79], v[178:181], v[232:235], v[76:79]
	v_mfma_f32_16x16x32_bf16 v[72:75], v[166:169], v[236:239], v[72:75]
	v_mfma_f32_16x16x32_bf16 v[72:75], v[170:173], v[240:243], v[72:75]
	v_mfma_f32_16x16x32_bf16 v[68:71], v[174:177], v[236:239], v[68:71]
	v_mfma_f32_16x16x32_bf16 v[68:71], v[178:181], v[240:243], v[68:71]
	s_setprio 0
	s_barrier
; #define PG8_STAGE(bufoff, gbase, voff) do { _Pragma("unroll") for (int _i = 0; _i < 2; ++_i) \
;         __builtin_amdgcn_global_load_lds((const unsigned*)((const char*)(gbase) + (voff)[_i]), (PG8_LAS unsigned*)(lds + (bufoff) + ldsw + _i * 8192), 16, 0, 0); } while (0)
; #define PG8_LDA(dst, b, h) do { _Pragma("unroll") for (int m = 0; m < 4; ++m) _Pragma("unroll") for (int k = 0; k < 2; ++k) dst[m][k] = *(const PG8_LAS bf16x8*)(lds + PG8_SA(b, h) + aoff + m * 2048 + k * 1024); } while (0)
; #define PG8_MMA(ai, bj, At, Bt) do { __builtin_amdgcn_s_setprio(1); _Pragma("unroll") for (int m = 0; m < 4; ++m) _Pragma("unroll") for (int n = 0; n < 2; ++n) _Pragma("unroll") for (int k = 0; k < 2; ++k) \
;         acc[ai][bj][m][n] = __builtin_amdgcn_mfma_f32_16x16x32_bf16(Bt[n][k], At[m][k], acc[ai][bj][m][n], 0, 0, 0); __builtin_amdgcn_s_setprio(0); } while (0)
; #define PG8_WAIT_V(n) asm volatile("s_waitcnt vmcnt(" #n ")" ::: "memory")
; #define PG8_WAIT_L(n) asm volatile("s_waitcnt lgkmcnt(" #n ")" ::: "memory")
; #define PG8_BAR __builtin_amdgcn_s_barrier()
; #define PG8_SCHED __builtin_amdgcn_sched_barrier(0)
; template <class Epi, class Sched, bool ALIGN_EPI = false, bool SP2 = false>
; __device__ __forceinline__ void gemm_phase(PG8_LAS unsigned char* lds, const Gemm g, const Sched& S, const Epi& E) {
;     ...
;         for (int t = 0; t < nt; t += 2) {
;     ...
;             PG8_LDA(At, 1, 1); PG8_STAGE(PG8_SB(1, 0), b3, voffB); PG8_STAGE(PG8_SB(1, 1), b3 + hstep, voffB); PG8_STAGE(PG8_SA(1, 0), a3, voffA);
;             PG8_WAIT_V(8); PG8_WAIT_L(0); PG8_BAR; PG8_MMA(1, 0, At, B0); PG8_MMA(1, 1, At, B1); PG8_BAR; PG8_SCHED;
	s_add_i32 s18, s44, s23
	v_lshl_add_u64 v[144:145], v[144:145], 0, s[34:35]
	s_mov_b32 m0, s18
	ds_read_b128 v[198:201], v148 offset:49152
	ds_read_b128 v[202:205], v148 offset:50176
	ds_read_b128 v[220:223], v148 offset:51200
	ds_read_b128 v[224:227], v148 offset:52224
	ds_read_b128 v[228:231], v148 offset:53248
	ds_read_b128 v[232:235], v148 offset:54272
	ds_read_b128 v[236:239], v148 offset:55296
	ds_read_b128 v[240:243], v148 offset:56320
	global_load_lds_dwordx4 v[144:145], off
	s_add_i32 m0, s18, 0x2000
	s_add_u32 s16, s16, 0x80080
	v_lshl_add_u64 v[144:145], v[184:185], 0, s[34:35]
	s_addc_u32 s17, s17, 0
	s_add_i32 s18, s45, s23
	global_load_lds_dwordx4 v[144:145], off
	v_lshl_add_u64 v[144:145], s[16:17], 0, v[2:3]
	s_mov_b32 m0, s18
	s_nop 0
	global_load_lds_dwordx4 v[144:145], off
	v_lshl_add_u64 v[144:145], s[16:17], 0, v[132:133]
	s_add_i32 m0, s18, 0x2000
	s_nop 0
	global_load_lds_dwordx4 v[144:145], off
	v_lshl_add_u64 v[144:145], v[186:187], 0, s[34:35]
	s_mov_b32 m0, s28
	s_nop 0
	global_load_lds_dwordx4 v[144:145], off
	v_lshl_add_u64 v[144:145], v[196:197], 0, s[34:35]
	s_mov_b32 m0, s29
	s_nop 0
	global_load_lds_dwordx4 v[144:145], off
	s_waitcnt vmcnt(8)
	s_waitcnt lgkmcnt(0)
	s_barrier
	s_setprio 1
	s_waitcnt lgkmcnt(0)
	v_mfma_f32_16x16x32_bf16 v[64:67], v[150:153], v[198:201], v[64:67]
	v_mfma_f32_16x16x32_bf16 v[64:67], v[154:157], v[202:205], v[64:67]
	v_mfma_f32_16x16x32_bf16 v[60:63], v[158:161], v[198:201], v[60:63]
	v_mfma_f32_16x16x32_bf16 v[60:63], v[162:165], v[202:205], v[60:63]
	v_mfma_f32_16x16x32_bf16 v[56:59], v[150:153], v[220:223], v[56:59]
	v_mfma_f32_16x16x32_bf16 v[56:59], v[154:157], v[224:227], v[56:59]
	v_mfma_f32_16x16x32_bf16 v[48:51], v[158:161], v[220:223], v[48:51]
	v_mfma_f32_16x16x32_bf16 v[48:51], v[162:165], v[224:227], v[48:51]
	v_mfma_f32_16x16x32_bf16 v[40:43], v[150:153], v[228:231], v[40:43]
	v_mfma_f32_16x16x32_bf16 v[40:43], v[154:157], v[232:235], v[40:43]
	v_mfma_f32_16x16x32_bf16 v[32:35], v[158:161], v[228:231], v[32:35]
	v_mfma_f32_16x16x32_bf16 v[32:35], v[162:165], v[232:235], v[32:35]
	v_mfma_f32_16x16x32_bf16 v[24:27], v[150:153], v[236:239], v[24:27]
	v_mfma_f32_16x16x32_bf16 v[24:27], v[154:157], v[240:243], v[24:27]
	v_mfma_f32_16x16x32_bf16 v[16:19], v[158:161], v[236:239], v[16:19]
	v_mfma_f32_16x16x32_bf16 v[16:19], v[162:165], v[240:243], v[16:19]
	s_setprio 0
	s_setprio 1
	v_mfma_f32_16x16x32_bf16 v[52:55], v[166:169], v[198:201], v[52:55]
	v_mfma_f32_16x16x32_bf16 v[52:55], v[170:173], v[202:205], v[52:55]
	v_mfma_f32_16x16x32_bf16 v[44:47], v[174:177], v[198:201], v[44:47]
	v_mfma_f32_16x16x32_bf16 v[44:47], v[178:181], v[202:205], v[44:47]
	v_mfma_f32_16x16x32_bf16 v[36:39], v[166:169], v[220:223], v[36:39]
	v_mfma_f32_16x16x32_bf16 v[36:39], v[170:173], v[224:227], v[36:39]
	v_mfma_f32_16x16x32_bf16 v[28:31], v[174:177], v[220:223], v[28:31]
	v_mfma_f32_16x16x32_bf16 v[28:31], v[178:181], v[224:227], v[28:31]
	v_mfma_f32_16x16x32_bf16 v[20:23], v[166:169], v[228:231], v[20:23]
	v_mfma_f32_16x16x32_bf16 v[20:23], v[170:173], v[232:235], v[20:23]
	v_mfma_f32_16x16x32_bf16 v[12:15], v[174:177], v[228:231], v[12:15]
	v_mfma_f32_16x16x32_bf16 v[12:15], v[178:181], v[232:235], v[12:15]
	v_mfma_f32_16x16x32_bf16 v[8:11], v[166:169], v[236:239], v[8:11]
	v_mfma_f32_16x16x32_bf16 v[8:11], v[170:173], v[240:243], v[8:11]
	v_mfma_f32_16x16x32_bf16 v[4:7], v[174:177], v[236:239], v[4:7]
	v_mfma_f32_16x16x32_bf16 v[4:7], v[178:181], v[240:243], v[4:7]
	s_setprio 0
	s_barrier
	s_add_i32 s43, s43, 2
	s_add_u32 s14, s14, 0x100
	s_addc_u32 s15, s15, 0
	s_add_u32 s41, s41, 0x100
	s_addc_u32 s42, s42, 0
	s_cmp_gt_u32 s43, 29
	s_cbranch_scc0 .LBB11_913
	s_and_b64 vcc, exec, s[4:5]
	s_cbranch_vccz .LBB11_916
	s_barrier

; #define PG8_STAGE(bufoff, gbase, voff) do { _Pragma("unroll") for (int _i = 0; _i < 2; ++_i) \
;         __builtin_amdgcn_global_load_lds((const unsigned*)((const char*)(gbase) + (voff)[_i]), (PG8_LAS unsigned*)(lds + (bufoff) + ldsw + _i * 8192), 16, 0, 0); } while (0)
; #define PG8_LDA(dst, b, h) do { _Pragma("unroll") for (int m = 0; m < 4; ++m) _Pragma("unroll") for (int k = 0; k < 2; ++k) dst[m][k] = *(const PG8_LAS bf16x8*)(lds + PG8_SA(b, h) + aoff + m * 2048 + k * 1024); } while (0)
; #define PG8_LDB(dst, b, h) do { _Pragma("unroll") for (int n = 0; n < 2; ++n) _Pragma("unroll") for (int k = 0; k < 2; ++k) dst[n][k] = *(const PG8_LAS bf16x8*)(lds + PG8_SB(b, h) + boff + n * 2048 + k * 1024); } while (0)
; #define PG8_MMA(ai, bj, At, Bt) do { __builtin_amdgcn_s_setprio(1); _Pragma("unroll") for (int m = 0; m < 4; ++m) _Pragma("unroll") for (int n = 0; n < 2; ++n) _Pragma("unroll") for (int k = 0; k < 2; ++k) \
;         acc[ai][bj][m][n] = __builtin_amdgcn_mfma_f32_16x16x32_bf16(Bt[n][k], At[m][k], acc[ai][bj][m][n], 0, 0, 0); __builtin_amdgcn_s_setprio(0); } while (0)
; #define PG8_WAIT_V(n) asm volatile("s_waitcnt vmcnt(" #n ")" ::: "memory")
; #define PG8_WAIT_L(n) asm volatile("s_waitcnt lgkmcnt(" #n ")" ::: "memory")
; #define PG8_BAR __builtin_amdgcn_s_barrier()
; #define PG8_SCHED __builtin_amdgcn_sched_barrier(0)
; template <class Epi, class Sched, bool ALIGN_EPI = false, bool SP2 = false>
; __device__ __forceinline__ void gemm_phase(PG8_LAS unsigned char* lds, const Gemm g, const Sched& S, const Epi& E) {
;     ...
;             PG8_LDB(B0, 0, 0); PG8_LDB(B1, 0, 1); PG8_SCHED; PG8_LDA(At, 0, 0); PG8_STAGE(PG8_SA(1, 1), a1 + hstep, voffA);
;             PG8_WAIT_V(8); PG8_WAIT_L(0); PG8_BAR; PG8_MMA(0, 0, At, B0); PG8_MMA(0, 1, At, B1); PG8_BAR; PG8_SCHED;
;             PG8_LDA(At, 0, 1); PG8_STAGE(PG8_SB(0, 0), b2, voffB); PG8_STAGE(PG8_SB(0, 1), b2 + hstep, voffB); PG8_STAGE(PG8_SA(0, 0), a2, voffA);
;             PG8_WAIT_V(8); PG8_WAIT_L(0); PG8_BAR; PG8_MMA(1, 0, At, B0); PG8_MMA(1, 1, At, B1); PG8_BAR; PG8_SCHED;
.LBB11_1071:
	s_add_u32 s16, s14, 0xfff80080
	s_addc_u32 s17, s15, -1
	s_add_i32 s46, 0, 0x10000
	s_cmp_eq_u32 s45, 28
	s_cselect_b32 s19, s9, s17
	s_cselect_b32 s18, s41, s16
	v_add_u32_e32 v2, s46, v168
	s_cselect_b32 s17, s7, s44
	s_cselect_b32 s16, s42, s43
	s_add_i32 s48, 0, 0x14000
	ds_read_b128 v[132:135], v2
	ds_read_b128 v[136:139], v2 offset:1024
	ds_read_b128 v[140:143], v2 offset:2048
	ds_read_b128 v[144:147], v2 offset:3072
	v_add_u32_e32 v2, s48, v168
	ds_read_b128 v[170:173], v2
	ds_read_b128 v[174:177], v2 offset:1024
	ds_read_b128 v[178:181], v2 offset:2048
	ds_read_b128 v[198:201], v2 offset:3072
	v_lshl_add_u64 v[166:167], s[14:15], 0, v[162:163]
	s_add_i32 m0, s25, 0xc000
	ds_read_b128 v[202:205], v169
	ds_read_b128 v[220:223], v169 offset:1024
	ds_read_b128 v[224:227], v169 offset:2048
	ds_read_b128 v[228:231], v169 offset:3072
	ds_read_b128 v[232:235], v169 offset:4096
	ds_read_b128 v[236:239], v169 offset:5120
	ds_read_b128 v[240:243], v169 offset:6144
	ds_read_b128 v[244:247], v169 offset:7168
	global_load_lds_dwordx4 v[166:167], off
	v_lshl_add_u64 v[166:167], s[14:15], 0, v[164:165]
	s_add_i32 m0, s25, 0xe000
	s_nop 0
	global_load_lds_dwordx4 v[166:167], off
	s_waitcnt vmcnt(8)
	s_waitcnt lgkmcnt(0)
	s_barrier
	s_setprio 1
	s_waitcnt lgkmcnt(0)
	v_mfma_f32_16x16x32_bf16 v[128:131], v[132:135], v[202:205], v[128:131]
	v_mfma_f32_16x16x32_bf16 v[128:131], v[136:139], v[220:223], v[128:131]
	v_mfma_f32_16x16x32_bf16 v[124:127], v[140:143], v[202:205], v[124:127]
	v_mfma_f32_16x16x32_bf16 v[124:127], v[144:147], v[220:223], v[124:127]
	v_mfma_f32_16x16x32_bf16 v[120:123], v[132:135], v[224:227], v[120:123]
	v_mfma_f32_16x16x32_bf16 v[120:123], v[136:139], v[228:231], v[120:123]
	v_mfma_f32_16x16x32_bf16 v[112:115], v[140:143], v[224:227], v[112:115]
	v_mfma_f32_16x16x32_bf16 v[112:115], v[144:147], v[228:231], v[112:115]
	v_mfma_f32_16x16x32_bf16 v[104:107], v[132:135], v[232:235], v[104:107]
	v_mfma_f32_16x16x32_bf16 v[104:107], v[136:139], v[236:239], v[104:107]
	v_mfma_f32_16x16x32_bf16 v[96:99], v[140:143], v[232:235], v[96:99]
	v_mfma_f32_16x16x32_bf16 v[96:99], v[144:147], v[236:239], v[96:99]
	v_mfma_f32_16x16x32_bf16 v[88:91], v[132:135], v[240:243], v[88:91]
	v_mfma_f32_16x16x32_bf16 v[88:91], v[136:139], v[244:247], v[88:91]
	v_mfma_f32_16x16x32_bf16 v[80:83], v[140:143], v[240:243], v[80:83]
	v_mfma_f32_16x16x32_bf16 v[80:83], v[144:147], v[244:247], v[80:83]
	s_setprio 0
	s_setprio 1
	v_mfma_f32_16x16x32_bf16 v[116:119], v[170:173], v[202:205], v[116:119]
	v_mfma_f32_16x16x32_bf16 v[116:119], v[174:177], v[220:223], v[116:119]
	v_mfma_f32_16x16x32_bf16 v[108:111], v[178:181], v[202:205], v[108:111]
	v_mfma_f32_16x16x32_bf16 v[108:111], v[198:201], v[220:223], v[108:111]
	v_mfma_f32_16x16x32_bf16 v[100:103], v[170:173], v[224:227], v[100:103]
	v_mfma_f32_16x16x32_bf16 v[100:103], v[174:177], v[228:231], v[100:103]
	v_mfma_f32_16x16x32_bf16 v[92:95], v[178:181], v[224:227], v[92:95]
	v_mfma_f32_16x16x32_bf16 v[92:95], v[198:201], v[228:231], v[92:95]
	v_mfma_f32_16x16x32_bf16 v[84:87], v[170:173], v[232:235], v[84:87]
	v_mfma_f32_16x16x32_bf16 v[84:87], v[174:177], v[236:239], v[84:87]
	v_mfma_f32_16x16x32_bf16 v[76:79], v[178:181], v[232:235], v[76:79]
	v_mfma_f32_16x16x32_bf16 v[76:79], v[198:201], v[236:239], v[76:79]
	v_mfma_f32_16x16x32_bf16 v[72:75], v[170:173], v[240:243], v[72:75]
	v_mfma_f32_16x16x32_bf16 v[72:75], v[174:177], v[244:247], v[72:75]
	v_mfma_f32_16x16x32_bf16 v[68:71], v[178:181], v[240:243], v[68:71]
	v_mfma_f32_16x16x32_bf16 v[68:71], v[198:201], v[244:247], v[68:71]
	s_setprio 0
	s_barrier
	s_add_i32 s46, s46, s24
	v_lshl_add_u64 v[166:167], s[16:17], 0, v[154:155]
	s_mov_b32 m0, s46
	ds_read_b128 v[202:205], v169 offset:16384
	ds_read_b128 v[220:223], v169 offset:17408
	ds_read_b128 v[224:227], v169 offset:18432
	ds_read_b128 v[228:231], v169 offset:19456
	ds_read_b128 v[232:235], v169 offset:20480
	ds_read_b128 v[236:239], v169 offset:21504
	ds_read_b128 v[240:243], v169 offset:22528
	ds_read_b128 v[244:247], v169 offset:23552
	global_load_lds_dwordx4 v[166:167], off
	s_add_i32 m0, s46, 0x2000
	s_add_u32 s46, s16, 0x80000
	v_lshl_add_u64 v[196:197], s[16:17], 0, v[150:151]
	s_addc_u32 s47, s17, 0
	s_add_i32 s48, s48, s24
	global_load_lds_dwordx4 v[196:197], off
	v_lshl_add_u64 v[206:207], s[46:47], 0, v[154:155]
	s_mov_b32 m0, s48
	v_lshl_add_u64 v[184:185], s[18:19], 0, v[152:153]
	global_load_lds_dwordx4 v[206:207], off
	v_lshl_add_u64 v[206:207], s[46:47], 0, v[150:151]
	s_add_i32 m0, s48, 0x2000
	s_nop 0
	global_load_lds_dwordx4 v[206:207], off
	v_lshl_add_u64 v[206:207], s[18:19], 0, v[156:157]
	s_mov_b32 m0, s25
	s_nop 0
	global_load_lds_dwordx4 v[206:207], off
	s_mov_b32 m0, s26
	s_nop 0
	global_load_lds_dwordx4 v[184:185], off
	s_waitcnt vmcnt(8)
	s_waitcnt lgkmcnt(0)
	s_barrier
; #define PG8_STAGE(bufoff, gbase, voff) do { _Pragma("unroll") for (int _i = 0; _i < 2; ++_i) \
;         __builtin_amdgcn_global_load_lds((const unsigned*)((const char*)(gbase) + (voff)[_i]), (PG8_LAS unsigned*)(lds + (bufoff) + ldsw + _i * 8192), 16, 0, 0); } while (0)
; #define PG8_LDA(dst, b, h) do { _Pragma("unroll") for (int m = 0; m < 4; ++m) _Pragma("unroll") for (int k = 0; k < 2; ++k) dst[m][k] = *(const PG8_LAS bf16x8*)(lds + PG8_SA(b, h) + aoff + m * 2048 + k * 1024); } while (0)
; #define PG8_LDB(dst, b, h) do { _Pragma("unroll") for (int n = 0; n < 2; ++n) _Pragma("unroll") for (int k = 0; k < 2; ++k) dst[n][k] = *(const PG8_LAS bf16x8*)(lds + PG8_SB(b, h) + boff + n * 2048 + k * 1024); } while (0)
; #define PG8_MMA(ai, bj, At, Bt) do { __builtin_amdgcn_s_setprio(1); _Pragma("unroll") for (int m = 0; m < 4; ++m) _Pragma("unroll") for (int n = 0; n < 2; ++n) _Pragma("unroll") for (int k = 0; k < 2; ++k) \
;         acc[ai][bj][m][n] = __builtin_amdgcn_mfma_f32_16x16x32_bf16(Bt[n][k], At[m][k], acc[ai][bj][m][n], 0, 0, 0); __builtin_amdgcn_s_setprio(0); } while (0)
; #define PG8_WAIT_V(n) asm volatile("s_waitcnt vmcnt(" #n ")" ::: "memory")
; #define PG8_WAIT_L(n) asm volatile("s_waitcnt lgkmcnt(" #n ")" ::: "memory")
; #define PG8_BAR __builtin_amdgcn_s_barrier()
; #define PG8_SCHED __builtin_amdgcn_sched_barrier(0)
; template <class Epi, class Sched, bool ALIGN_EPI = false, bool SP2 = false>
; __device__ __forceinline__ void gemm_phase(PG8_LAS unsigned char* lds, const Gemm g, const Sched& S, const Epi& E) {
;     ...
;             PG8_WAIT_V(8); PG8_WAIT_L(0); PG8_BAR; PG8_MMA(0, 0, At, B0); PG8_MMA(0, 1, At, B1); PG8_BAR; PG8_SCHED;
;             PG8_LDA(At, 0, 1); PG8_STAGE(PG8_SB(0, 0), b2, voffB); PG8_STAGE(PG8_SB(0, 1), b2 + hstep, voffB); PG8_STAGE(PG8_SA(0, 0), a2, voffA);
;             PG8_WAIT_V(8); PG8_WAIT_L(0); PG8_BAR; PG8_MMA(1, 0, At, B0); PG8_MMA(1, 1, At, B1); PG8_BAR; PG8_SCHED;
;             PG8_LDB(B0, 1, 0); PG8_LDB(B1, 1, 1); PG8_SCHED; PG8_LDA(At, 1, 0); PG8_STAGE(PG8_SA(0, 1), a2 + hstep, voffA);
;             PG8_WAIT_V(8); PG8_WAIT_L(0); PG8_BAR; PG8_MMA(0, 0, At, B0); PG8_MMA(0, 1, At, B1); PG8_BAR; PG8_SCHED;
	s_setprio 1
	s_waitcnt lgkmcnt(0)
	v_mfma_f32_16x16x32_bf16 v[64:67], v[132:135], v[202:205], v[64:67]
	v_mfma_f32_16x16x32_bf16 v[64:67], v[136:139], v[220:223], v[64:67]
	v_mfma_f32_16x16x32_bf16 v[60:63], v[140:143], v[202:205], v[60:63]
	v_mfma_f32_16x16x32_bf16 v[60:63], v[144:147], v[220:223], v[60:63]
	v_mfma_f32_16x16x32_bf16 v[56:59], v[132:135], v[224:227], v[56:59]
	v_mfma_f32_16x16x32_bf16 v[56:59], v[136:139], v[228:231], v[56:59]
	v_mfma_f32_16x16x32_bf16 v[48:51], v[140:143], v[224:227], v[48:51]
	v_mfma_f32_16x16x32_bf16 v[48:51], v[144:147], v[228:231], v[48:51]
	v_mfma_f32_16x16x32_bf16 v[40:43], v[132:135], v[232:235], v[40:43]
	v_mfma_f32_16x16x32_bf16 v[40:43], v[136:139], v[236:239], v[40:43]
	v_mfma_f32_16x16x32_bf16 v[32:35], v[140:143], v[232:235], v[32:35]
	v_mfma_f32_16x16x32_bf16 v[32:35], v[144:147], v[236:239], v[32:35]
	v_mfma_f32_16x16x32_bf16 v[24:27], v[132:135], v[240:243], v[24:27]
	v_mfma_f32_16x16x32_bf16 v[24:27], v[136:139], v[244:247], v[24:27]
	v_mfma_f32_16x16x32_bf16 v[16:19], v[140:143], v[240:243], v[16:19]
	v_mfma_f32_16x16x32_bf16 v[16:19], v[144:147], v[244:247], v[16:19]
	s_setprio 0
	s_setprio 1
	v_mfma_f32_16x16x32_bf16 v[52:55], v[170:173], v[202:205], v[52:55]
	v_mfma_f32_16x16x32_bf16 v[52:55], v[174:177], v[220:223], v[52:55]
	v_mfma_f32_16x16x32_bf16 v[44:47], v[178:181], v[202:205], v[44:47]
	v_mfma_f32_16x16x32_bf16 v[44:47], v[198:201], v[220:223], v[44:47]
	v_mfma_f32_16x16x32_bf16 v[36:39], v[170:173], v[224:227], v[36:39]
	v_mfma_f32_16x16x32_bf16 v[36:39], v[174:177], v[228:231], v[36:39]
	v_mfma_f32_16x16x32_bf16 v[28:31], v[178:181], v[224:227], v[28:31]
	v_mfma_f32_16x16x32_bf16 v[28:31], v[198:201], v[228:231], v[28:31]
	v_mfma_f32_16x16x32_bf16 v[20:23], v[170:173], v[232:235], v[20:23]
	v_mfma_f32_16x16x32_bf16 v[20:23], v[174:177], v[236:239], v[20:23]
	v_mfma_f32_16x16x32_bf16 v[12:15], v[178:181], v[232:235], v[12:15]
	v_mfma_f32_16x16x32_bf16 v[12:15], v[198:201], v[236:239], v[12:15]
	v_mfma_f32_16x16x32_bf16 v[8:11], v[170:173], v[240:243], v[8:11]
	v_mfma_f32_16x16x32_bf16 v[8:11], v[174:177], v[244:247], v[8:11]
	v_mfma_f32_16x16x32_bf16 v[4:7], v[178:181], v[240:243], v[4:7]
	v_mfma_f32_16x16x32_bf16 v[4:7], v[198:201], v[244:247], v[4:7]
	s_setprio 0
	s_barrier
	s_add_i32 s46, 0, 0x18000
	v_add_u32_e32 v2, s46, v168
	s_add_i32 s47, 0, 0x1c000
	ds_read_b128 v[132:135], v2
	ds_read_b128 v[136:139], v2 offset:1024
	ds_read_b128 v[140:143], v2 offset:2048
	ds_read_b128 v[144:147], v2 offset:3072
	v_add_u32_e32 v2, s47, v168
	ds_read_b128 v[170:173], v2
	ds_read_b128 v[174:177], v2 offset:1024
	ds_read_b128 v[178:181], v2 offset:2048
	ds_read_b128 v[198:201], v2 offset:3072
	s_add_u32 s18, s18, 0x80000
	s_addc_u32 s19, s19, 0
	s_mov_b32 m0, s27
	v_lshl_add_u64 v[186:187], s[18:19], 0, v[156:157]
	ds_read_b128 v[202:205], v169 offset:32768
	ds_read_b128 v[220:223], v169 offset:33792
	ds_read_b128 v[224:227], v169 offset:34816
	ds_read_b128 v[228:231], v169 offset:35840
	ds_read_b128 v[232:235], v169 offset:36864
	ds_read_b128 v[236:239], v169 offset:37888
	ds_read_b128 v[240:243], v169 offset:38912
	ds_read_b128 v[244:247], v169 offset:39936
	global_load_lds_dwordx4 v[186:187], off
	v_lshl_add_u64 v[186:187], s[18:19], 0, v[152:153]
	s_mov_b32 m0, s28
	s_nop 0
	global_load_lds_dwordx4 v[186:187], off
	s_waitcnt vmcnt(8)
	s_waitcnt lgkmcnt(0)
	s_barrier
	s_setprio 1
	s_waitcnt lgkmcnt(0)
	v_mfma_f32_16x16x32_bf16 v[128:131], v[132:135], v[202:205], v[128:131]
	v_mfma_f32_16x16x32_bf16 v[128:131], v[136:139], v[220:223], v[128:131]
	v_mfma_f32_16x16x32_bf16 v[124:127], v[140:143], v[202:205], v[124:127]
	v_mfma_f32_16x16x32_bf16 v[124:127], v[144:147], v[220:223], v[124:127]
	v_mfma_f32_16x16x32_bf16 v[120:123], v[132:135], v[224:227], v[120:123]
	v_mfma_f32_16x16x32_bf16 v[120:123], v[136:139], v[228:231], v[120:123]
	v_mfma_f32_16x16x32_bf16 v[112:115], v[140:143], v[224:227], v[112:115]
	v_mfma_f32_16x16x32_bf16 v[112:115], v[144:147], v[228:231], v[112:115]
	v_mfma_f32_16x16x32_bf16 v[104:107], v[132:135], v[232:235], v[104:107]
	v_mfma_f32_16x16x32_bf16 v[104:107], v[136:139], v[236:239], v[104:107]
	v_mfma_f32_16x16x32_bf16 v[96:99], v[140:143], v[232:235], v[96:99]
	v_mfma_f32_16x16x32_bf16 v[96:99], v[144:147], v[236:239], v[96:99]
	v_mfma_f32_16x16x32_bf16 v[88:91], v[132:135], v[240:243], v[88:91]
	v_mfma_f32_16x16x32_bf16 v[88:91], v[136:139], v[244:247], v[88:91]
	v_mfma_f32_16x16x32_bf16 v[80:83], v[140:143], v[240:243], v[80:83]
	v_mfma_f32_16x16x32_bf16 v[80:83], v[144:147], v[244:247], v[80:83]
	s_setprio 0
	s_setprio 1
	v_mfma_f32_16x16x32_bf16 v[116:119], v[170:173], v[202:205], v[116:119]
	v_mfma_f32_16x16x32_bf16 v[116:119], v[174:177], v[220:223], v[116:119]
	v_mfma_f32_16x16x32_bf16 v[108:111], v[178:181], v[202:205], v[108:111]
	v_mfma_f32_16x16x32_bf16 v[108:111], v[198:201], v[220:223], v[108:111]
	v_mfma_f32_16x16x32_bf16 v[100:103], v[170:173], v[224:227], v[100:103]
	v_mfma_f32_16x16x32_bf16 v[100:103], v[174:177], v[228:231], v[100:103]
	v_mfma_f32_16x16x32_bf16 v[92:95], v[178:181], v[224:227], v[92:95]
	v_mfma_f32_16x16x32_bf16 v[92:95], v[198:201], v[228:231], v[92:95]
	v_mfma_f32_16x16x32_bf16 v[84:87], v[170:173], v[232:235], v[84:87]
	v_mfma_f32_16x16x32_bf16 v[84:87], v[174:177], v[236:239], v[84:87]
	v_mfma_f32_16x16x32_bf16 v[76:79], v[178:181], v[232:235], v[76:79]
	v_mfma_f32_16x16x32_bf16 v[76:79], v[198:201], v[236:239], v[76:79]
	v_mfma_f32_16x16x32_bf16 v[72:75], v[170:173], v[240:243], v[72:75]
	v_mfma_f32_16x16x32_bf16 v[72:75], v[174:177], v[244:247], v[72:75]
	v_mfma_f32_16x16x32_bf16 v[68:71], v[178:181], v[240:243], v[68:71]
	v_mfma_f32_16x16x32_bf16 v[68:71], v[198:201], v[244:247], v[68:71]
	s_setprio 0
	s_barrier
; #define PG8_STAGE(bufoff, gbase, voff) do { _Pragma("unroll") for (int _i = 0; _i < 2; ++_i) \
;         __builtin_amdgcn_global_load_lds((const unsigned*)((const char*)(gbase) + (voff)[_i]), (PG8_LAS unsigned*)(lds + (bufoff) + ldsw + _i * 8192), 16, 0, 0); } while (0)
; #define PG8_LDA(dst, b, h) do { _Pragma("unroll") for (int m = 0; m < 4; ++m) _Pragma("unroll") for (int k = 0; k < 2; ++k) dst[m][k] = *(const PG8_LAS bf16x8*)(lds + PG8_SA(b, h) + aoff + m * 2048 + k * 1024); } while (0)
; #define PG8_MMA(ai, bj, At, Bt) do { __builtin_amdgcn_s_setprio(1); _Pragma("unroll") for (int m = 0; m < 4; ++m) _Pragma("unroll") for (int n = 0; n < 2; ++n) _Pragma("unroll") for (int k = 0; k < 2; ++k) \
;         acc[ai][bj][m][n] = __builtin_amdgcn_mfma_f32_16x16x32_bf16(Bt[n][k], At[m][k], acc[ai][bj][m][n], 0, 0, 0); __builtin_amdgcn_s_setprio(0); } while (0)
; #define PG8_WAIT_V(n) asm volatile("s_waitcnt vmcnt(" #n ")" ::: "memory")
; #define PG8_WAIT_L(n) asm volatile("s_waitcnt lgkmcnt(" #n ")" ::: "memory")
; #define PG8_BAR __builtin_amdgcn_s_barrier()
; #define PG8_SCHED __builtin_amdgcn_sched_barrier(0)
; template <class Epi, class Sched, bool ALIGN_EPI = false, bool SP2 = false>
; __device__ __forceinline__ void gemm_phase(PG8_LAS unsigned char* lds, const Gemm g, const Sched& S, const Epi& E) {
;     ...
;         for (int t = 0; t < nt; t += 2) {
;     ...
;             PG8_LDA(At, 1, 1); PG8_STAGE(PG8_SB(1, 0), b3, voffB); PG8_STAGE(PG8_SB(1, 1), b3 + hstep, voffB); PG8_STAGE(PG8_SA(1, 0), a3, voffA);
;             PG8_WAIT_V(8); PG8_WAIT_L(0); PG8_BAR; PG8_MMA(1, 0, At, B0); PG8_MMA(1, 1, At, B1); PG8_BAR; PG8_SCHED;
	s_add_i32 s18, s46, s24
	v_lshl_add_u64 v[166:167], v[166:167], 0, s[34:35]
	s_mov_b32 m0, s18
	ds_read_b128 v[202:205], v169 offset:49152
	ds_read_b128 v[220:223], v169 offset:50176
	ds_read_b128 v[224:227], v169 offset:51200
	ds_read_b128 v[228:231], v169 offset:52224
	ds_read_b128 v[232:235], v169 offset:53248
	ds_read_b128 v[236:239], v169 offset:54272
	ds_read_b128 v[240:243], v169 offset:55296
	ds_read_b128 v[244:247], v169 offset:56320
	global_load_lds_dwordx4 v[166:167], off
	s_add_i32 m0, s18, 0x2000
	s_add_u32 s16, s16, 0x80080
	v_lshl_add_u64 v[166:167], v[196:197], 0, s[34:35]
	s_addc_u32 s17, s17, 0
	s_add_i32 s18, s47, s24
	global_load_lds_dwordx4 v[166:167], off
	v_lshl_add_u64 v[166:167], s[16:17], 0, v[154:155]
	s_mov_b32 m0, s18
	s_nop 0
	global_load_lds_dwordx4 v[166:167], off
	v_lshl_add_u64 v[166:167], s[16:17], 0, v[150:151]
	s_add_i32 m0, s18, 0x2000
	s_nop 0
	global_load_lds_dwordx4 v[166:167], off
	v_lshl_add_u64 v[166:167], v[206:207], 0, s[34:35]
	s_mov_b32 m0, s33
	s_nop 0
	global_load_lds_dwordx4 v[166:167], off
	v_lshl_add_u64 v[166:167], v[184:185], 0, s[34:35]
	s_mov_b32 m0, s38
	s_nop 0
	global_load_lds_dwordx4 v[166:167], off
	s_waitcnt vmcnt(8)
	s_waitcnt lgkmcnt(0)
	s_barrier
	s_setprio 1
	s_waitcnt lgkmcnt(0)
	v_mfma_f32_16x16x32_bf16 v[64:67], v[132:135], v[202:205], v[64:67]
	v_mfma_f32_16x16x32_bf16 v[64:67], v[136:139], v[220:223], v[64:67]
	v_mfma_f32_16x16x32_bf16 v[60:63], v[140:143], v[202:205], v[60:63]
	v_mfma_f32_16x16x32_bf16 v[60:63], v[144:147], v[220:223], v[60:63]
	v_mfma_f32_16x16x32_bf16 v[56:59], v[132:135], v[224:227], v[56:59]
	v_mfma_f32_16x16x32_bf16 v[56:59], v[136:139], v[228:231], v[56:59]
	v_mfma_f32_16x16x32_bf16 v[48:51], v[140:143], v[224:227], v[48:51]
	v_mfma_f32_16x16x32_bf16 v[48:51], v[144:147], v[228:231], v[48:51]
	v_mfma_f32_16x16x32_bf16 v[40:43], v[132:135], v[232:235], v[40:43]
	v_mfma_f32_16x16x32_bf16 v[40:43], v[136:139], v[236:239], v[40:43]
	v_mfma_f32_16x16x32_bf16 v[32:35], v[140:143], v[232:235], v[32:35]
	v_mfma_f32_16x16x32_bf16 v[32:35], v[144:147], v[236:239], v[32:35]
	v_mfma_f32_16x16x32_bf16 v[24:27], v[132:135], v[240:243], v[24:27]
	v_mfma_f32_16x16x32_bf16 v[24:27], v[136:139], v[244:247], v[24:27]
	v_mfma_f32_16x16x32_bf16 v[16:19], v[140:143], v[240:243], v[16:19]
	v_mfma_f32_16x16x32_bf16 v[16:19], v[144:147], v[244:247], v[16:19]
	s_setprio 0
	s_setprio 1
	v_mfma_f32_16x16x32_bf16 v[52:55], v[170:173], v[202:205], v[52:55]
	v_mfma_f32_16x16x32_bf16 v[52:55], v[174:177], v[220:223], v[52:55]
	v_mfma_f32_16x16x32_bf16 v[44:47], v[178:181], v[202:205], v[44:47]
	v_mfma_f32_16x16x32_bf16 v[44:47], v[198:201], v[220:223], v[44:47]
	v_mfma_f32_16x16x32_bf16 v[36:39], v[170:173], v[224:227], v[36:39]
	v_mfma_f32_16x16x32_bf16 v[36:39], v[174:177], v[228:231], v[36:39]
	v_mfma_f32_16x16x32_bf16 v[28:31], v[178:181], v[224:227], v[28:31]
	v_mfma_f32_16x16x32_bf16 v[28:31], v[198:201], v[228:231], v[28:31]
	v_mfma_f32_16x16x32_bf16 v[20:23], v[170:173], v[232:235], v[20:23]
	v_mfma_f32_16x16x32_bf16 v[20:23], v[174:177], v[236:239], v[20:23]
	v_mfma_f32_16x16x32_bf16 v[12:15], v[178:181], v[232:235], v[12:15]
	v_mfma_f32_16x16x32_bf16 v[12:15], v[198:201], v[236:239], v[12:15]
	v_mfma_f32_16x16x32_bf16 v[8:11], v[170:173], v[240:243], v[8:11]
	v_mfma_f32_16x16x32_bf16 v[8:11], v[174:177], v[244:247], v[8:11]
	v_mfma_f32_16x16x32_bf16 v[4:7], v[178:181], v[240:243], v[4:7]
	v_mfma_f32_16x16x32_bf16 v[4:7], v[198:201], v[244:247], v[4:7]
	s_setprio 0
	s_barrier
	s_add_i32 s45, s45, 2
	s_add_u32 s14, s14, 0x100
	s_addc_u32 s15, s15, 0
	s_add_u32 s43, s43, 0x100
	s_addc_u32 s44, s44, 0
	s_cmp_gt_u32 s45, 29
	s_cbranch_scc0 .LBB11_1071
	s_and_b64 vcc, exec, s[4:5]
	s_cbranch_vccz .LBB11_1074
	s_barrier

; #define PG8_STAGE(bufoff, gbase, voff) do { _Pragma("unroll") for (int _i = 0; _i < 2; ++_i) \
;         __builtin_amdgcn_global_load_lds((const unsigned*)((const char*)(gbase) + (voff)[_i]), (PG8_LAS unsigned*)(lds + (bufoff) + ldsw + _i * 8192), 16, 0, 0); } while (0)
; #define PG8_LDA(dst, b, h) do { _Pragma("unroll") for (int m = 0; m < 4; ++m) _Pragma("unroll") for (int k = 0; k < 2; ++k) dst[m][k] = *(const PG8_LAS bf16x8*)(lds + PG8_SA(b, h) + aoff + m * 2048 + k * 1024); } while (0)
; #define PG8_LDB(dst, b, h) do { _Pragma("unroll") for (int n = 0; n < 2; ++n) _Pragma("unroll") for (int k = 0; k < 2; ++k) dst[n][k] = *(const PG8_LAS bf16x8*)(lds + PG8_SB(b, h) + boff + n * 2048 + k * 1024); } while (0)
; #define PG8_MMA(ai, bj, At, Bt) do { __builtin_amdgcn_s_setprio(1); _Pragma("unroll") for (int m = 0; m < 4; ++m) _Pragma("unroll") for (int n = 0; n < 2; ++n) _Pragma("unroll") for (int k = 0; k < 2; ++k) \
;         acc[ai][bj][m][n] = __builtin_amdgcn_mfma_f32_16x16x32_bf16(Bt[n][k], At[m][k], acc[ai][bj][m][n], 0, 0, 0); __builtin_amdgcn_s_setprio(0); } while (0)
; #define PG8_WAIT_V(n) asm volatile("s_waitcnt vmcnt(" #n ")" ::: "memory")
; #define PG8_WAIT_L(n) asm volatile("s_waitcnt lgkmcnt(" #n ")" ::: "memory")
; #define PG8_BAR __builtin_amdgcn_s_barrier()
; #define PG8_SCHED __builtin_amdgcn_sched_barrier(0)
; template <class Epi, class Sched, bool ALIGN_EPI = false, bool SP2 = false>
; __device__ __forceinline__ void gemm_phase(PG8_LAS unsigned char* lds, const Gemm g, const Sched& S, const Epi& E) {
;     ...
;             PG8_LDB(B0, 0, 0); PG8_LDB(B1, 0, 1); PG8_SCHED; PG8_LDA(At, 0, 0); PG8_STAGE(PG8_SA(1, 1), a1 + hstep, voffA);
;             PG8_WAIT_V(8); PG8_WAIT_L(0); PG8_BAR; PG8_MMA(0, 0, At, B0); PG8_MMA(0, 1, At, B1); PG8_BAR; PG8_SCHED;
;             PG8_LDA(At, 0, 1); PG8_STAGE(PG8_SB(0, 0), b2, voffB); PG8_STAGE(PG8_SB(0, 1), b2 + hstep, voffB); PG8_STAGE(PG8_SA(0, 0), a2, voffA);
.LBB11_1896:
	s_add_i32 s56, s22, 2
	s_add_u32 s57, s16, s20
	s_addc_u32 s23, s17, s21
	s_add_u32 s58, s14, s20
	s_addc_u32 s59, s15, s21
	s_add_i32 s60, 0, 0x10000
	s_cmp_eq_u32 s49, s22
	s_cselect_b32 s23, s5, s23
	s_cselect_b32 s22, s4, s57
	s_cselect_b32 s59, s19, s59
	s_cselect_b32 s58, s18, s58
	s_add_i32 s57, 0, 0x14000
	v_add_u32_e32 v156, s60, v1
	v_add_u32_e32 v174, s57, v1
	ds_read_b128 v[144:147], v156
	ds_read_b128 v[148:151], v156 offset:1024
	ds_read_b128 v[152:155], v156 offset:2048
	ds_read_b128 v[156:159], v156 offset:3072
	ds_read_b128 v[160:163], v174
	ds_read_b128 v[166:169], v174 offset:1024
	ds_read_b128 v[170:173], v174 offset:2048
	ds_read_b128 v[174:177], v174 offset:3072
	v_lshl_add_u64 v[184:185], s[16:17], 0, v[140:141]
	s_add_i32 m0, s45, 0xc000
	ds_read_b128 v[178:181], v143
	ds_read_b128 v[198:201], v143 offset:1024
	ds_read_b128 v[202:205], v143 offset:2048
	ds_read_b128 v[220:223], v143 offset:3072
	ds_read_b128 v[224:227], v143 offset:4096
	ds_read_b128 v[228:231], v143 offset:5120
	ds_read_b128 v[232:235], v143 offset:6144
	ds_read_b128 v[236:239], v143 offset:7168
	global_load_lds_dwordx4 v[184:185], off
	v_lshl_add_u64 v[184:185], s[16:17], 0, v[138:139]
	s_add_i32 m0, s45, 0xe000
	s_nop 0
	global_load_lds_dwordx4 v[184:185], off
	s_waitcnt vmcnt(8)
	s_waitcnt lgkmcnt(0)
	s_barrier
	s_setprio 1
	s_waitcnt lgkmcnt(0)
	v_mfma_f32_16x16x32_bf16 v[100:103], v[144:147], v[178:181], v[100:103]
	v_mfma_f32_16x16x32_bf16 v[100:103], v[148:151], v[198:201], v[100:103]
	v_mfma_f32_16x16x32_bf16 v[68:71], v[152:155], v[178:181], v[68:71]
	v_mfma_f32_16x16x32_bf16 v[68:71], v[156:159], v[198:201], v[68:71]
	v_mfma_f32_16x16x32_bf16 v[116:119], v[144:147], v[202:205], v[116:119]
	v_mfma_f32_16x16x32_bf16 v[116:119], v[148:151], v[220:223], v[116:119]
	v_mfma_f32_16x16x32_bf16 v[80:83], v[152:155], v[202:205], v[80:83]
	v_mfma_f32_16x16x32_bf16 v[80:83], v[156:159], v[220:223], v[80:83]
	v_mfma_f32_16x16x32_bf16 v[124:127], v[144:147], v[224:227], v[124:127]
	v_mfma_f32_16x16x32_bf16 v[124:127], v[148:151], v[228:231], v[124:127]
	v_mfma_f32_16x16x32_bf16 v[104:107], v[152:155], v[224:227], v[104:107]
	v_mfma_f32_16x16x32_bf16 v[104:107], v[156:159], v[228:231], v[104:107]
	v_mfma_f32_16x16x32_bf16 v[128:131], v[144:147], v[232:235], v[128:131]
	v_mfma_f32_16x16x32_bf16 v[128:131], v[148:151], v[236:239], v[128:131]
	v_mfma_f32_16x16x32_bf16 v[120:123], v[152:155], v[232:235], v[120:123]
	v_mfma_f32_16x16x32_bf16 v[120:123], v[156:159], v[236:239], v[120:123]
	s_setprio 0
	s_setprio 1
	v_mfma_f32_16x16x32_bf16 v[16:19], v[160:163], v[178:181], v[16:19]
	v_mfma_f32_16x16x32_bf16 v[16:19], v[166:169], v[198:201], v[16:19]
	v_mfma_f32_16x16x32_bf16 v[4:7], v[170:173], v[178:181], v[4:7]
	v_mfma_f32_16x16x32_bf16 v[4:7], v[174:177], v[198:201], v[4:7]
	v_mfma_f32_16x16x32_bf16 v[32:35], v[160:163], v[202:205], v[32:35]
	v_mfma_f32_16x16x32_bf16 v[32:35], v[166:169], v[220:223], v[32:35]
	v_mfma_f32_16x16x32_bf16 v[8:11], v[170:173], v[202:205], v[8:11]
	v_mfma_f32_16x16x32_bf16 v[8:11], v[174:177], v[220:223], v[8:11]
	v_mfma_f32_16x16x32_bf16 v[48:51], v[160:163], v[224:227], v[48:51]
	v_mfma_f32_16x16x32_bf16 v[48:51], v[166:169], v[228:231], v[48:51]
	v_mfma_f32_16x16x32_bf16 v[12:15], v[170:173], v[224:227], v[12:15]
	v_mfma_f32_16x16x32_bf16 v[12:15], v[174:177], v[228:231], v[12:15]
	v_mfma_f32_16x16x32_bf16 v[76:79], v[160:163], v[232:235], v[76:79]
	v_mfma_f32_16x16x32_bf16 v[76:79], v[166:169], v[236:239], v[76:79]
	v_mfma_f32_16x16x32_bf16 v[24:27], v[170:173], v[232:235], v[24:27]
	v_mfma_f32_16x16x32_bf16 v[24:27], v[174:177], v[236:239], v[24:27]
	s_setprio 0
	s_barrier
	s_add_i32 s60, s60, s13
	v_lshl_add_u64 v[184:185], s[58:59], 0, v[2:3]
	s_mov_b32 m0, s60
	ds_read_b128 v[178:181], v143 offset:16384
	ds_read_b128 v[198:201], v143 offset:17408
	ds_read_b128 v[202:205], v143 offset:18432
	ds_read_b128 v[220:223], v143 offset:19456
	ds_read_b128 v[224:227], v143 offset:20480
	ds_read_b128 v[228:231], v143 offset:21504
	ds_read_b128 v[232:235], v143 offset:22528
	ds_read_b128 v[236:239], v143 offset:23552
	global_load_lds_dwordx4 v[184:185], off
	s_add_i32 m0, s60, 0x2000
	v_lshl_add_u64 v[186:187], s[58:59], 0, v[132:133]
	s_add_u32 s58, s58, s33
	s_addc_u32 s59, s59, 0
	s_add_i32 s57, s57, s13
	global_load_lds_dwordx4 v[186:187], off
	v_lshl_add_u64 v[196:197], s[58:59], 0, v[2:3]
	s_mov_b32 m0, s57
	v_lshl_add_u64 v[206:207], s[58:59], 0, v[132:133]
	global_load_lds_dwordx4 v[196:197], off
	s_add_i32 m0, s57, 0x2000
	v_lshl_add_u64 v[240:241], s[22:23], 0, v[2:3]
	global_load_lds_dwordx4 v[206:207], off
	s_mov_b32 m0, s45
	v_lshl_add_u64 v[242:243], s[22:23], 0, v[132:133]
	global_load_lds_dwordx4 v[240:241], off
	s_mov_b32 m0, s46
	s_nop 0
	global_load_lds_dwordx4 v[242:243], off
	s_waitcnt vmcnt(8)
	s_waitcnt lgkmcnt(0)
	s_barrier
; #define PG8_STAGE(bufoff, gbase, voff) do { _Pragma("unroll") for (int _i = 0; _i < 2; ++_i) \
;         __builtin_amdgcn_global_load_lds((const unsigned*)((const char*)(gbase) + (voff)[_i]), (PG8_LAS unsigned*)(lds + (bufoff) + ldsw + _i * 8192), 16, 0, 0); } while (0)
; #define PG8_LDA(dst, b, h) do { _Pragma("unroll") for (int m = 0; m < 4; ++m) _Pragma("unroll") for (int k = 0; k < 2; ++k) dst[m][k] = *(const PG8_LAS bf16x8*)(lds + PG8_SA(b, h) + aoff + m * 2048 + k * 1024); } while (0)
; #define PG8_LDB(dst, b, h) do { _Pragma("unroll") for (int n = 0; n < 2; ++n) _Pragma("unroll") for (int k = 0; k < 2; ++k) dst[n][k] = *(const PG8_LAS bf16x8*)(lds + PG8_SB(b, h) + boff + n * 2048 + k * 1024); } while (0)
; #define PG8_MMA(ai, bj, At, Bt) do { __builtin_amdgcn_s_setprio(1); _Pragma("unroll") for (int m = 0; m < 4; ++m) _Pragma("unroll") for (int n = 0; n < 2; ++n) _Pragma("unroll") for (int k = 0; k < 2; ++k) \
;         acc[ai][bj][m][n] = __builtin_amdgcn_mfma_f32_16x16x32_bf16(Bt[n][k], At[m][k], acc[ai][bj][m][n], 0, 0, 0); __builtin_amdgcn_s_setprio(0); } while (0)
; #define PG8_WAIT_V(n) asm volatile("s_waitcnt vmcnt(" #n ")" ::: "memory")
; #define PG8_WAIT_L(n) asm volatile("s_waitcnt lgkmcnt(" #n ")" ::: "memory")
; #define PG8_BAR __builtin_amdgcn_s_barrier()
; #define PG8_SCHED __builtin_amdgcn_sched_barrier(0)
; template <class Epi, class Sched, bool ALIGN_EPI = false, bool SP2 = false>
; __device__ __forceinline__ void gemm_phase(PG8_LAS unsigned char* lds, const Gemm g, const Sched& S, const Epi& E) {
;     ...
;             PG8_WAIT_V(8); PG8_WAIT_L(0); PG8_BAR; PG8_MMA(1, 0, At, B0); PG8_MMA(1, 1, At, B1); PG8_BAR; PG8_SCHED;
;             PG8_LDB(B0, 1, 0); PG8_LDB(B1, 1, 1); PG8_SCHED; PG8_LDA(At, 1, 0); PG8_STAGE(PG8_SA(0, 1), a2 + hstep, voffA);
;             PG8_WAIT_V(8); PG8_WAIT_L(0); PG8_BAR; PG8_MMA(0, 0, At, B0); PG8_MMA(0, 1, At, B1); PG8_BAR; PG8_SCHED;
	s_setprio 1
	s_waitcnt lgkmcnt(0)
	v_mfma_f32_16x16x32_bf16 v[108:111], v[144:147], v[178:181], v[108:111]
	v_mfma_f32_16x16x32_bf16 v[108:111], v[148:151], v[198:201], v[108:111]
	v_mfma_f32_16x16x32_bf16 v[112:115], v[152:155], v[178:181], v[112:115]
	v_mfma_f32_16x16x32_bf16 v[112:115], v[156:159], v[198:201], v[112:115]
	v_mfma_f32_16x16x32_bf16 v[88:91], v[144:147], v[202:205], v[88:91]
	v_mfma_f32_16x16x32_bf16 v[88:91], v[148:151], v[220:223], v[88:91]
	v_mfma_f32_16x16x32_bf16 v[92:95], v[152:155], v[202:205], v[92:95]
	v_mfma_f32_16x16x32_bf16 v[92:95], v[156:159], v[220:223], v[92:95]
	v_mfma_f32_16x16x32_bf16 v[60:63], v[144:147], v[224:227], v[60:63]
	v_mfma_f32_16x16x32_bf16 v[60:63], v[148:151], v[228:231], v[60:63]
	v_mfma_f32_16x16x32_bf16 v[64:67], v[152:155], v[224:227], v[64:67]
	v_mfma_f32_16x16x32_bf16 v[64:67], v[156:159], v[228:231], v[64:67]
	v_mfma_f32_16x16x32_bf16 v[36:39], v[144:147], v[232:235], v[36:39]
	v_mfma_f32_16x16x32_bf16 v[36:39], v[148:151], v[236:239], v[36:39]
	v_mfma_f32_16x16x32_bf16 v[40:43], v[152:155], v[232:235], v[40:43]
	v_mfma_f32_16x16x32_bf16 v[40:43], v[156:159], v[236:239], v[40:43]
	s_setprio 0
	s_setprio 1
	v_mfma_f32_16x16x32_bf16 v[96:99], v[160:163], v[178:181], v[96:99]
	v_mfma_f32_16x16x32_bf16 v[96:99], v[166:169], v[198:201], v[96:99]
	v_mfma_f32_16x16x32_bf16 v[44:47], v[170:173], v[178:181], v[44:47]
	v_mfma_f32_16x16x32_bf16 v[44:47], v[174:177], v[198:201], v[44:47]
	v_mfma_f32_16x16x32_bf16 v[84:87], v[160:163], v[202:205], v[84:87]
	v_mfma_f32_16x16x32_bf16 v[84:87], v[166:169], v[220:223], v[84:87]
	v_mfma_f32_16x16x32_bf16 v[72:75], v[170:173], v[202:205], v[72:75]
	v_mfma_f32_16x16x32_bf16 v[72:75], v[174:177], v[220:223], v[72:75]
	v_mfma_f32_16x16x32_bf16 v[56:59], v[160:163], v[224:227], v[56:59]
	v_mfma_f32_16x16x32_bf16 v[56:59], v[166:169], v[228:231], v[56:59]
	v_mfma_f32_16x16x32_bf16 v[52:55], v[170:173], v[224:227], v[52:55]
	v_mfma_f32_16x16x32_bf16 v[52:55], v[174:177], v[228:231], v[52:55]
	v_mfma_f32_16x16x32_bf16 v[28:31], v[160:163], v[232:235], v[28:31]
	v_mfma_f32_16x16x32_bf16 v[28:31], v[166:169], v[236:239], v[28:31]
	v_mfma_f32_16x16x32_bf16 v[20:23], v[170:173], v[232:235], v[20:23]
	v_mfma_f32_16x16x32_bf16 v[20:23], v[174:177], v[236:239], v[20:23]
	s_setprio 0
	s_barrier
	s_add_i32 s57, 0, 0x18000
	s_add_i32 s58, 0, 0x1c000
	v_add_u32_e32 v156, s57, v1
	v_add_u32_e32 v174, s58, v1
	ds_read_b128 v[144:147], v156
	ds_read_b128 v[148:151], v156 offset:1024
	ds_read_b128 v[152:155], v156 offset:2048
	ds_read_b128 v[156:159], v156 offset:3072
	ds_read_b128 v[160:163], v174
	ds_read_b128 v[166:169], v174 offset:1024
	ds_read_b128 v[170:173], v174 offset:2048
	ds_read_b128 v[174:177], v174 offset:3072
	s_add_u32 s22, s22, s33
	s_addc_u32 s23, s23, 0
	s_mov_b32 m0, s47
	v_lshl_add_u64 v[244:245], s[22:23], 0, v[2:3]
	ds_read_b128 v[178:181], v143 offset:32768
	ds_read_b128 v[198:201], v143 offset:33792
	ds_read_b128 v[202:205], v143 offset:34816
	ds_read_b128 v[220:223], v143 offset:35840
	ds_read_b128 v[224:227], v143 offset:36864
	ds_read_b128 v[228:231], v143 offset:37888
	ds_read_b128 v[232:235], v143 offset:38912
	ds_read_b128 v[236:239], v143 offset:39936
	global_load_lds_dwordx4 v[244:245], off
	v_lshl_add_u64 v[244:245], s[22:23], 0, v[132:133]
	s_mov_b32 m0, s48
	s_nop 0
	global_load_lds_dwordx4 v[244:245], off
	s_waitcnt vmcnt(8)
	s_waitcnt lgkmcnt(0)
	s_barrier
	s_setprio 1
	s_waitcnt lgkmcnt(0)
	v_mfma_f32_16x16x32_bf16 v[100:103], v[144:147], v[178:181], v[100:103]
	v_mfma_f32_16x16x32_bf16 v[100:103], v[148:151], v[198:201], v[100:103]
	v_mfma_f32_16x16x32_bf16 v[68:71], v[152:155], v[178:181], v[68:71]
	v_mfma_f32_16x16x32_bf16 v[68:71], v[156:159], v[198:201], v[68:71]
	v_mfma_f32_16x16x32_bf16 v[116:119], v[144:147], v[202:205], v[116:119]
	v_mfma_f32_16x16x32_bf16 v[116:119], v[148:151], v[220:223], v[116:119]
	v_mfma_f32_16x16x32_bf16 v[80:83], v[152:155], v[202:205], v[80:83]
	v_mfma_f32_16x16x32_bf16 v[80:83], v[156:159], v[220:223], v[80:83]
	v_mfma_f32_16x16x32_bf16 v[124:127], v[144:147], v[224:227], v[124:127]
	v_mfma_f32_16x16x32_bf16 v[124:127], v[148:151], v[228:231], v[124:127]
	v_mfma_f32_16x16x32_bf16 v[104:107], v[152:155], v[224:227], v[104:107]
	v_mfma_f32_16x16x32_bf16 v[104:107], v[156:159], v[228:231], v[104:107]
	v_mfma_f32_16x16x32_bf16 v[128:131], v[144:147], v[232:235], v[128:131]
	v_mfma_f32_16x16x32_bf16 v[128:131], v[148:151], v[236:239], v[128:131]
	v_mfma_f32_16x16x32_bf16 v[120:123], v[152:155], v[232:235], v[120:123]
	v_mfma_f32_16x16x32_bf16 v[120:123], v[156:159], v[236:239], v[120:123]
	s_setprio 0
	s_setprio 1
	v_mfma_f32_16x16x32_bf16 v[16:19], v[160:163], v[178:181], v[16:19]
	v_mfma_f32_16x16x32_bf16 v[16:19], v[166:169], v[198:201], v[16:19]
	v_mfma_f32_16x16x32_bf16 v[4:7], v[170:173], v[178:181], v[4:7]
	v_mfma_f32_16x16x32_bf16 v[4:7], v[174:177], v[198:201], v[4:7]
	v_mfma_f32_16x16x32_bf16 v[32:35], v[160:163], v[202:205], v[32:35]
	v_mfma_f32_16x16x32_bf16 v[32:35], v[166:169], v[220:223], v[32:35]
	v_mfma_f32_16x16x32_bf16 v[8:11], v[170:173], v[202:205], v[8:11]
	v_mfma_f32_16x16x32_bf16 v[8:11], v[174:177], v[220:223], v[8:11]
	v_mfma_f32_16x16x32_bf16 v[48:51], v[160:163], v[224:227], v[48:51]
	v_mfma_f32_16x16x32_bf16 v[48:51], v[166:169], v[228:231], v[48:51]
	v_mfma_f32_16x16x32_bf16 v[12:15], v[170:173], v[224:227], v[12:15]
	v_mfma_f32_16x16x32_bf16 v[12:15], v[174:177], v[228:231], v[12:15]
	v_mfma_f32_16x16x32_bf16 v[76:79], v[160:163], v[232:235], v[76:79]
	v_mfma_f32_16x16x32_bf16 v[76:79], v[166:169], v[236:239], v[76:79]
	v_mfma_f32_16x16x32_bf16 v[24:27], v[170:173], v[232:235], v[24:27]
	v_mfma_f32_16x16x32_bf16 v[24:27], v[174:177], v[236:239], v[24:27]
	s_setprio 0
	s_barrier
; #define PG8_STAGE(bufoff, gbase, voff) do { _Pragma("unroll") for (int _i = 0; _i < 2; ++_i) \
;         __builtin_amdgcn_global_load_lds((const unsigned*)((const char*)(gbase) + (voff)[_i]), (PG8_LAS unsigned*)(lds + (bufoff) + ldsw + _i * 8192), 16, 0, 0); } while (0)
; #define PG8_LDA(dst, b, h) do { _Pragma("unroll") for (int m = 0; m < 4; ++m) _Pragma("unroll") for (int k = 0; k < 2; ++k) dst[m][k] = *(const PG8_LAS bf16x8*)(lds + PG8_SA(b, h) + aoff + m * 2048 + k * 1024); } while (0)
; #define PG8_MMA(ai, bj, At, Bt) do { __builtin_amdgcn_s_setprio(1); _Pragma("unroll") for (int m = 0; m < 4; ++m) _Pragma("unroll") for (int n = 0; n < 2; ++n) _Pragma("unroll") for (int k = 0; k < 2; ++k) \
;         acc[ai][bj][m][n] = __builtin_amdgcn_mfma_f32_16x16x32_bf16(Bt[n][k], At[m][k], acc[ai][bj][m][n], 0, 0, 0); __builtin_amdgcn_s_setprio(0); } while (0)
; #define PG8_WAIT_V(n) asm volatile("s_waitcnt vmcnt(" #n ")" ::: "memory")
; #define PG8_WAIT_L(n) asm volatile("s_waitcnt lgkmcnt(" #n ")" ::: "memory")
; #define PG8_BAR __builtin_amdgcn_s_barrier()
; #define PG8_SCHED __builtin_amdgcn_sched_barrier(0)
; template <class Epi, class Sched, bool ALIGN_EPI = false, bool SP2 = false>
; __device__ __forceinline__ void gemm_phase(PG8_LAS unsigned char* lds, const Gemm g, const Sched& S, const Epi& E) {
;     ...
;             PG8_LDA(At, 1, 1); PG8_STAGE(PG8_SB(1, 0), b3, voffB); PG8_STAGE(PG8_SB(1, 1), b3 + hstep, voffB); PG8_STAGE(PG8_SA(1, 0), a3, voffA);
;             PG8_WAIT_V(8); PG8_WAIT_L(0); PG8_BAR; PG8_MMA(1, 0, At, B0); PG8_MMA(1, 1, At, B1); PG8_BAR; PG8_SCHED;
;     ...
;         if (!has_next) break;
; #pragma unroll
;         for (int a = 0; a < 2; ++a)
; #pragma unroll
;             for (int b = 0; b < 2; ++b)
; #pragma unroll
;                 for (int m = 0; m < 4; ++m)
; #pragma unroll
;                     for (int n = 0; n < 2; ++n) acc[a][b][m][n] = (f32x4){0.f, 0.f, 0.f, 0.f};
;         cur = nxt; cA = nA; cB = nB; ++ui;
	s_add_i32 s22, s57, s13
	v_lshl_add_u64 v[184:185], v[184:185], 0, s[34:35]
	s_mov_b32 m0, s22
	ds_read_b128 v[178:181], v143 offset:49152
	ds_read_b128 v[198:201], v143 offset:50176
	ds_read_b128 v[202:205], v143 offset:51200
	ds_read_b128 v[220:223], v143 offset:52224
	ds_read_b128 v[224:227], v143 offset:53248
	ds_read_b128 v[228:231], v143 offset:54272
	ds_read_b128 v[232:235], v143 offset:55296
	ds_read_b128 v[236:239], v143 offset:56320
	global_load_lds_dwordx4 v[184:185], off
	v_lshl_add_u64 v[184:185], v[186:187], 0, s[34:35]
	s_add_i32 m0, s22, 0x2000
	s_add_i32 s22, s58, s13
	global_load_lds_dwordx4 v[184:185], off
	v_lshl_add_u64 v[184:185], v[196:197], 0, s[34:35]
	s_mov_b32 m0, s22
	s_nop 0
	global_load_lds_dwordx4 v[184:185], off
	v_lshl_add_u64 v[184:185], v[206:207], 0, s[34:35]
	s_add_i32 m0, s22, 0x2000
	s_nop 0
	global_load_lds_dwordx4 v[184:185], off
	v_lshl_add_u64 v[184:185], v[240:241], 0, s[34:35]
	s_mov_b32 m0, s50
	s_nop 0
	global_load_lds_dwordx4 v[184:185], off
	v_lshl_add_u64 v[184:185], v[242:243], 0, s[34:35]
	s_mov_b32 m0, s51
	s_nop 0
	global_load_lds_dwordx4 v[184:185], off
	s_waitcnt vmcnt(8)
	s_waitcnt lgkmcnt(0)
	s_barrier
	s_setprio 1
	s_waitcnt lgkmcnt(0)
	v_mfma_f32_16x16x32_bf16 v[108:111], v[144:147], v[178:181], v[108:111]
	v_mfma_f32_16x16x32_bf16 v[108:111], v[148:151], v[198:201], v[108:111]
	v_mfma_f32_16x16x32_bf16 v[112:115], v[152:155], v[178:181], v[112:115]
	v_mfma_f32_16x16x32_bf16 v[112:115], v[156:159], v[198:201], v[112:115]
	v_mfma_f32_16x16x32_bf16 v[88:91], v[144:147], v[202:205], v[88:91]
	v_mfma_f32_16x16x32_bf16 v[88:91], v[148:151], v[220:223], v[88:91]
	v_mfma_f32_16x16x32_bf16 v[92:95], v[152:155], v[202:205], v[92:95]
	v_mfma_f32_16x16x32_bf16 v[92:95], v[156:159], v[220:223], v[92:95]
	v_mfma_f32_16x16x32_bf16 v[60:63], v[144:147], v[224:227], v[60:63]
	v_mfma_f32_16x16x32_bf16 v[60:63], v[148:151], v[228:231], v[60:63]
	v_mfma_f32_16x16x32_bf16 v[64:67], v[152:155], v[224:227], v[64:67]
	v_mfma_f32_16x16x32_bf16 v[64:67], v[156:159], v[228:231], v[64:67]
	v_mfma_f32_16x16x32_bf16 v[36:39], v[144:147], v[232:235], v[36:39]
	v_mfma_f32_16x16x32_bf16 v[36:39], v[148:151], v[236:239], v[36:39]
	v_mfma_f32_16x16x32_bf16 v[40:43], v[152:155], v[232:235], v[40:43]
	v_mfma_f32_16x16x32_bf16 v[40:43], v[156:159], v[236:239], v[40:43]
	s_setprio 0
	s_setprio 1
	v_mfma_f32_16x16x32_bf16 v[96:99], v[160:163], v[178:181], v[96:99]
	v_mfma_f32_16x16x32_bf16 v[96:99], v[166:169], v[198:201], v[96:99]
	v_mfma_f32_16x16x32_bf16 v[44:47], v[170:173], v[178:181], v[44:47]
	v_mfma_f32_16x16x32_bf16 v[44:47], v[174:177], v[198:201], v[44:47]
	v_mfma_f32_16x16x32_bf16 v[84:87], v[160:163], v[202:205], v[84:87]
	v_mfma_f32_16x16x32_bf16 v[84:87], v[166:169], v[220:223], v[84:87]
	v_mfma_f32_16x16x32_bf16 v[72:75], v[170:173], v[202:205], v[72:75]
	v_mfma_f32_16x16x32_bf16 v[72:75], v[174:177], v[220:223], v[72:75]
	v_mfma_f32_16x16x32_bf16 v[56:59], v[160:163], v[224:227], v[56:59]
	v_mfma_f32_16x16x32_bf16 v[56:59], v[166:169], v[228:231], v[56:59]
	v_mfma_f32_16x16x32_bf16 v[52:55], v[170:173], v[224:227], v[52:55]
	v_mfma_f32_16x16x32_bf16 v[52:55], v[174:177], v[228:231], v[52:55]
	v_mfma_f32_16x16x32_bf16 v[28:31], v[160:163], v[232:235], v[28:31]
	v_mfma_f32_16x16x32_bf16 v[28:31], v[166:169], v[236:239], v[28:31]
	v_mfma_f32_16x16x32_bf16 v[20:23], v[170:173], v[232:235], v[20:23]
	v_mfma_f32_16x16x32_bf16 v[20:23], v[174:177], v[236:239], v[20:23]
	s_setprio 0
	s_barrier
	s_add_u32 s20, s20, 0x100
	s_addc_u32 s21, s21, 0
	v_lshl_add_u64 v[140:141], v[140:141], 0, s[62:63]
	v_lshl_add_u64 v[138:139], v[138:139], 0, s[62:63]
	s_cmp_ge_u32 s56, s29
	s_mov_b32 s22, s56
	s_cbranch_scc0 .LBB11_1896
	s_and_b64 vcc, exec, s[38:39]
	s_cbranch_vccnz .LBB11_1884
	v_mov_b32_e32 v20, 0
	s_mov_b32 s42, s53
	s_mov_b32 s28, s54
	s_mov_b64 s[14:15], s[18:19]
	s_mov_b64 s[16:17], s[4:5]
	s_mov_b32 s52, s55
	v_mov_b32_e32 v21, v20
	v_mov_b32_e32 v22, v20
	v_mov_b32_e32 v23, v20
	v_mov_b32_e32 v28, v20
	v_mov_b32_e32 v29, v20
	v_mov_b32_e32 v30, v20
	v_mov_b32_e32 v31, v20
	v_mov_b32_e32 v52, v20
	v_mov_b32_e32 v53, v20
	v_mov_b32_e32 v54, v20
	v_mov_b32_e32 v55, v20
	v_mov_b32_e32 v56, v20
	v_mov_b32_e32 v57, v20
	v_mov_b32_e32 v58, v20
	v_mov_b32_e32 v59, v20
	v_mov_b32_e32 v72, v20
	v_mov_b32_e32 v73, v20
	v_mov_b32_e32 v74, v20
	v_mov_b32_e32 v75, v20
	v_mov_b32_e32 v84, v20
	v_mov_b32_e32 v85, v20
	v_mov_b32_e32 v86, v20
	v_mov_b32_e32 v87, v20
	v_mov_b32_e32 v44, v20
	v_mov_b32_e32 v45, v20
	v_mov_b32_e32 v46, v20
	v_mov_b32_e32 v47, v20
	v_mov_b32_e32 v96, v20
	v_mov_b32_e32 v97, v20
	v_mov_b32_e32 v98, v20
	v_mov_b32_e32 v99, v20
	v_mov_b32_e32 v40, v20
	v_mov_b32_e32 v41, v20
	v_mov_b32_e32 v42, v20
	v_mov_b32_e32 v43, v20
	v_mov_b32_e32 v36, v20
	v_mov_b32_e32 v37, v20
	v_mov_b32_e32 v38, v20
	v_mov_b32_e32 v39, v20
	v_mov_b32_e32 v64, v20
	v_mov_b32_e32 v65, v20
	v_mov_b32_e32 v66, v20
	v_mov_b32_e32 v67, v20
	v_mov_b32_e32 v60, v20
	v_mov_b32_e32 v61, v20
	v_mov_b32_e32 v62, v20
	v_mov_b32_e32 v63, v20
	v_mov_b32_e32 v92, v20
	v_mov_b32_e32 v93, v20
	v_mov_b32_e32 v94, v20
	v_mov_b32_e32 v95, v20
	v_mov_b32_e32 v88, v20
	v_mov_b32_e32 v89, v20
	v_mov_b32_e32 v90, v20
	v_mov_b32_e32 v91, v20
	v_mov_b32_e32 v112, v20
	v_mov_b32_e32 v113, v20
	v_mov_b32_e32 v114, v20
	v_mov_b32_e32 v115, v20
	v_mov_b32_e32 v108, v20
	v_mov_b32_e32 v109, v20
	v_mov_b32_e32 v110, v20
	v_mov_b32_e32 v111, v20
	v_mov_b32_e32 v24, v20
	v_mov_b32_e32 v25, v20
	v_mov_b32_e32 v26, v20
	v_mov_b32_e32 v27, v20
	v_mov_b32_e32 v76, v20
	v_mov_b32_e32 v77, v20
	v_mov_b32_e32 v78, v20
	v_mov_b32_e32 v79, v20
	v_mov_b32_e32 v12, v20
	v_mov_b32_e32 v13, v20
	v_mov_b32_e32 v14, v20
	v_mov_b32_e32 v15, v20
	v_mov_b32_e32 v48, v20
	v_mov_b32_e32 v49, v20
	v_mov_b32_e32 v50, v20
	v_mov_b32_e32 v51, v20
	v_mov_b32_e32 v8, v20
	v_mov_b32_e32 v9, v20
	v_mov_b32_e32 v10, v20
	v_mov_b32_e32 v11, v20
	v_mov_b32_e32 v32, v20
	v_mov_b32_e32 v33, v20
	v_mov_b32_e32 v34, v20
	v_mov_b32_e32 v35, v20
	v_mov_b32_e32 v4, v20
	v_mov_b32_e32 v5, v20
	v_mov_b32_e32 v6, v20
	v_mov_b32_e32 v7, v20
	v_mov_b32_e32 v16, v20
	v_mov_b32_e32 v17, v20
	v_mov_b32_e32 v18, v20
	v_mov_b32_e32 v19, v20
	v_mov_b32_e32 v120, v20
	v_mov_b32_e32 v121, v20
	v_mov_b32_e32 v122, v20
	v_mov_b32_e32 v123, v20
	v_mov_b32_e32 v128, v20
	v_mov_b32_e32 v129, v20
	v_mov_b32_e32 v130, v20
	v_mov_b32_e32 v131, v20
	v_mov_b32_e32 v104, v20
	v_mov_b32_e32 v105, v20
	v_mov_b32_e32 v106, v20
	v_mov_b32_e32 v107, v20
	v_mov_b32_e32 v124, v20
	v_mov_b32_e32 v125, v20
	v_mov_b32_e32 v126, v20
	v_mov_b32_e32 v127, v20
	v_mov_b32_e32 v80, v20
	v_mov_b32_e32 v81, v20
	v_mov_b32_e32 v82, v20
	v_mov_b32_e32 v83, v20
	v_mov_b32_e32 v116, v20
	v_mov_b32_e32 v117, v20
	v_mov_b32_e32 v118, v20
	v_mov_b32_e32 v119, v20
	v_mov_b32_e32 v68, v20
	v_mov_b32_e32 v69, v20
	v_mov_b32_e32 v70, v20
	v_mov_b32_e32 v71, v20
	v_mov_b32_e32 v100, v20
	v_mov_b32_e32 v101, v20
	v_mov_b32_e32 v102, v20
	v_mov_b32_e32 v103, v20
	s_branch .LBB11_1884
